# GEMM K-loops: drop mid-block setprio pair, raise prio before the pre-MFMA barrier, lower after the post-MFMA barrier
# speedup vs baseline: 1.0141x; 1.0141x over previous
.LBB8_266:
	ds_read_b128 v[146:149], v155
	ds_read_b128 v[158:161], v155 offset:1024
	ds_read_b128 v[162:165], v155 offset:2048
	ds_read_b128 v[166:169], v155 offset:3072
	ds_read_b128 v[170:173], v156
	ds_read_b128 v[174:177], v156 offset:1024
	ds_read_b128 v[178:181], v156 offset:2048
	ds_read_b128 v[182:185], v156 offset:3072
	s_add_u32 s28, s70, 0xfff00080
	s_addc_u32 s29, s71, -1
	s_cmp_eq_u32 s93, 60
	s_cselect_b32 s73, s17, s29
	s_cselect_b32 s72, s85, s28
	s_cselect_b32 s29, s15, s92
	s_cselect_b32 s28, s86, s87
	v_lshl_add_u64 v[150:151], s[70:71], 0, v[138:139]
	s_add_i32 m0, s69, 0xc000
	ds_read_b128 v[186:189], v157
	ds_read_b128 v[190:193], v157 offset:1024
	ds_read_b128 v[194:197], v157 offset:2048
	ds_read_b128 v[198:201], v157 offset:3072
	ds_read_b128 v[202:205], v157 offset:4096
	ds_read_b128 v[206:209], v157 offset:5120
	ds_read_b128 v[210:213], v157 offset:6144
	ds_read_b128 v[214:217], v157 offset:7168
	global_load_lds_dwordx4 v[150:151], off
	v_lshl_add_u64 v[150:151], s[70:71], 0, v[140:141]
	s_add_i32 m0, s69, 0xe000
	s_nop 0
	global_load_lds_dwordx4 v[150:151], off
	s_waitcnt vmcnt(8)
	s_waitcnt lgkmcnt(0)
	s_setprio 1
	s_barrier
	v_mfma_f32_16x16x32_bf16 v[124:127], v[146:149], v[186:189], v[124:127]
	v_mfma_f32_16x16x32_bf16 v[120:123], v[162:165], v[186:189], v[120:123]
	v_mfma_f32_16x16x32_bf16 v[116:119], v[146:149], v[194:197], v[116:119]
	v_mfma_f32_16x16x32_bf16 v[108:111], v[162:165], v[194:197], v[108:111]
	v_mfma_f32_16x16x32_bf16 v[100:103], v[146:149], v[202:205], v[100:103]
	v_mfma_f32_16x16x32_bf16 v[92:95], v[162:165], v[202:205], v[92:95]
	v_mfma_f32_16x16x32_bf16 v[84:87], v[146:149], v[210:213], v[84:87]
	v_mfma_f32_16x16x32_bf16 v[76:79], v[162:165], v[210:213], v[76:79]
	v_mfma_f32_16x16x32_bf16 v[124:127], v[158:161], v[190:193], v[124:127]
	v_mfma_f32_16x16x32_bf16 v[120:123], v[166:169], v[190:193], v[120:123]
	v_mfma_f32_16x16x32_bf16 v[116:119], v[158:161], v[198:201], v[116:119]
	v_mfma_f32_16x16x32_bf16 v[108:111], v[166:169], v[198:201], v[108:111]
	v_mfma_f32_16x16x32_bf16 v[100:103], v[158:161], v[206:209], v[100:103]
	v_mfma_f32_16x16x32_bf16 v[92:95], v[166:169], v[206:209], v[92:95]
	v_mfma_f32_16x16x32_bf16 v[84:87], v[158:161], v[214:217], v[84:87]
	v_mfma_f32_16x16x32_bf16 v[76:79], v[166:169], v[214:217], v[76:79]
	v_mfma_f32_16x16x32_bf16 v[112:115], v[170:173], v[186:189], v[112:115]
	v_mfma_f32_16x16x32_bf16 v[104:107], v[178:181], v[186:189], v[104:107]
	v_mfma_f32_16x16x32_bf16 v[96:99], v[170:173], v[194:197], v[96:99]
	v_mfma_f32_16x16x32_bf16 v[88:91], v[178:181], v[194:197], v[88:91]
	v_mfma_f32_16x16x32_bf16 v[80:83], v[170:173], v[202:205], v[80:83]
	v_mfma_f32_16x16x32_bf16 v[72:75], v[178:181], v[202:205], v[72:75]
	v_mfma_f32_16x16x32_bf16 v[68:71], v[170:173], v[210:213], v[68:71]
	v_mfma_f32_16x16x32_bf16 v[64:67], v[178:181], v[210:213], v[64:67]
	v_mfma_f32_16x16x32_bf16 v[112:115], v[174:177], v[190:193], v[112:115]
	v_mfma_f32_16x16x32_bf16 v[104:107], v[182:185], v[190:193], v[104:107]
	v_mfma_f32_16x16x32_bf16 v[96:99], v[174:177], v[198:201], v[96:99]
	v_mfma_f32_16x16x32_bf16 v[88:91], v[182:185], v[198:201], v[88:91]
	v_mfma_f32_16x16x32_bf16 v[80:83], v[174:177], v[206:209], v[80:83]
	v_mfma_f32_16x16x32_bf16 v[72:75], v[182:185], v[206:209], v[72:75]
	v_mfma_f32_16x16x32_bf16 v[68:71], v[174:177], v[214:217], v[68:71]
	v_mfma_f32_16x16x32_bf16 v[64:67], v[182:185], v[214:217], v[64:67]
	s_barrier
	s_setprio 0
	s_add_i32 s52, s81, s57
	v_lshl_add_u64 v[150:151], s[28:29], 0, v[132:133]
	s_mov_b32 m0, s52
	ds_read_b128 v[186:189], v157 offset:16384
	ds_read_b128 v[190:193], v157 offset:17408
	ds_read_b128 v[194:197], v157 offset:18432
	ds_read_b128 v[198:201], v157 offset:19456
	ds_read_b128 v[202:205], v157 offset:20480
	ds_read_b128 v[206:209], v157 offset:21504
	ds_read_b128 v[210:213], v157 offset:22528
	ds_read_b128 v[214:217], v157 offset:23552
	global_load_lds_dwordx4 v[150:151], off
	s_add_i32 m0, s52, 0x2000
	s_add_u32 s94, s28, 0x100000
	v_lshl_add_u64 v[218:219], s[28:29], 0, v[128:129]
	s_addc_u32 s95, s29, 0
	s_add_i32 s52, s82, s57
	global_load_lds_dwordx4 v[218:219], off
	v_lshl_add_u64 v[220:221], s[94:95], 0, v[132:133]
	s_mov_b32 m0, s52
	v_lshl_add_u64 v[222:223], s[72:73], 0, v[130:131]
	global_load_lds_dwordx4 v[220:221], off
	v_lshl_add_u64 v[220:221], s[94:95], 0, v[128:129]
	s_add_i32 m0, s52, 0x2000
	s_nop 0
	global_load_lds_dwordx4 v[220:221], off
	v_lshl_add_u64 v[220:221], s[72:73], 0, v[134:135]
	s_mov_b32 m0, s69
	s_nop 0
	global_load_lds_dwordx4 v[220:221], off
	s_mov_b32 m0, s74
	s_nop 0
	global_load_lds_dwordx4 v[222:223], off
	s_waitcnt vmcnt(8)
	s_waitcnt lgkmcnt(0)
	s_setprio 1
	s_barrier
	v_mfma_f32_16x16x32_bf16 v[60:63], v[146:149], v[186:189], v[60:63]
	v_mfma_f32_16x16x32_bf16 v[56:59], v[162:165], v[186:189], v[56:59]
	v_mfma_f32_16x16x32_bf16 v[52:55], v[146:149], v[194:197], v[52:55]
	v_mfma_f32_16x16x32_bf16 v[44:47], v[162:165], v[194:197], v[44:47]
	v_mfma_f32_16x16x32_bf16 v[36:39], v[146:149], v[202:205], v[36:39]
	v_mfma_f32_16x16x32_bf16 v[28:31], v[162:165], v[202:205], v[28:31]
	v_mfma_f32_16x16x32_bf16 v[20:23], v[146:149], v[210:213], v[20:23]
	v_mfma_f32_16x16x32_bf16 v[12:15], v[162:165], v[210:213], v[12:15]
	v_mfma_f32_16x16x32_bf16 v[60:63], v[158:161], v[190:193], v[60:63]
	v_mfma_f32_16x16x32_bf16 v[56:59], v[166:169], v[190:193], v[56:59]
	v_mfma_f32_16x16x32_bf16 v[52:55], v[158:161], v[198:201], v[52:55]
	v_mfma_f32_16x16x32_bf16 v[44:47], v[166:169], v[198:201], v[44:47]
	v_mfma_f32_16x16x32_bf16 v[36:39], v[158:161], v[206:209], v[36:39]
	v_mfma_f32_16x16x32_bf16 v[28:31], v[166:169], v[206:209], v[28:31]
	v_mfma_f32_16x16x32_bf16 v[20:23], v[158:161], v[214:217], v[20:23]
	v_mfma_f32_16x16x32_bf16 v[12:15], v[166:169], v[214:217], v[12:15]
	v_mfma_f32_16x16x32_bf16 v[48:51], v[170:173], v[186:189], v[48:51]
	v_mfma_f32_16x16x32_bf16 v[40:43], v[178:181], v[186:189], v[40:43]
	v_mfma_f32_16x16x32_bf16 v[32:35], v[170:173], v[194:197], v[32:35]
	v_mfma_f32_16x16x32_bf16 v[24:27], v[178:181], v[194:197], v[24:27]
	v_mfma_f32_16x16x32_bf16 v[16:19], v[170:173], v[202:205], v[16:19]
	v_mfma_f32_16x16x32_bf16 v[8:11], v[178:181], v[202:205], v[8:11]
	v_mfma_f32_16x16x32_bf16 v[4:7], v[170:173], v[210:213], v[4:7]
	v_mfma_f32_16x16x32_bf16 v[0:3], v[178:181], v[210:213], v[0:3]
	v_mfma_f32_16x16x32_bf16 v[48:51], v[174:177], v[190:193], v[48:51]
	v_mfma_f32_16x16x32_bf16 v[40:43], v[182:185], v[190:193], v[40:43]
	v_mfma_f32_16x16x32_bf16 v[32:35], v[174:177], v[198:201], v[32:35]
	v_mfma_f32_16x16x32_bf16 v[24:27], v[182:185], v[198:201], v[24:27]
	v_mfma_f32_16x16x32_bf16 v[16:19], v[174:177], v[206:209], v[16:19]
	v_mfma_f32_16x16x32_bf16 v[8:11], v[182:185], v[206:209], v[8:11]
	v_mfma_f32_16x16x32_bf16 v[4:7], v[174:177], v[214:217], v[4:7]
	v_mfma_f32_16x16x32_bf16 v[0:3], v[182:185], v[214:217], v[0:3]
	s_barrier
	s_setprio 0
	s_add_i32 s52, 0, 0x18000
	s_add_i32 s53, 0, 0x1c000
	v_add_u32_e32 v166, s52, v153
	v_add_u32_e32 v182, s53, v153
	ds_read_b128 v[146:149], v166
	ds_read_b128 v[158:161], v166 offset:1024
	ds_read_b128 v[162:165], v166 offset:2048
	ds_read_b128 v[166:169], v166 offset:3072
	ds_read_b128 v[170:173], v182
	ds_read_b128 v[174:177], v182 offset:1024
	ds_read_b128 v[178:181], v182 offset:2048
	ds_read_b128 v[182:185], v182 offset:3072
	s_add_u32 s72, s72, 0x100000
	s_addc_u32 s73, s73, 0
	s_mov_b32 m0, s75
	v_lshl_add_u64 v[224:225], s[72:73], 0, v[134:135]
	ds_read_b128 v[186:189], v157 offset:32768
	ds_read_b128 v[190:193], v157 offset:33792
	ds_read_b128 v[194:197], v157 offset:34816
	ds_read_b128 v[198:201], v157 offset:35840
	ds_read_b128 v[202:205], v157 offset:36864
	ds_read_b128 v[206:209], v157 offset:37888
	ds_read_b128 v[210:213], v157 offset:38912
	ds_read_b128 v[214:217], v157 offset:39936
	global_load_lds_dwordx4 v[224:225], off
	v_lshl_add_u64 v[224:225], s[72:73], 0, v[130:131]
	s_mov_b32 m0, s76
	s_nop 0
	global_load_lds_dwordx4 v[224:225], off
	s_waitcnt vmcnt(8)
	s_waitcnt lgkmcnt(0)
	s_setprio 1
	s_barrier
	v_mfma_f32_16x16x32_bf16 v[124:127], v[146:149], v[186:189], v[124:127]
	v_mfma_f32_16x16x32_bf16 v[120:123], v[162:165], v[186:189], v[120:123]
	v_mfma_f32_16x16x32_bf16 v[116:119], v[146:149], v[194:197], v[116:119]
	v_mfma_f32_16x16x32_bf16 v[108:111], v[162:165], v[194:197], v[108:111]
	v_mfma_f32_16x16x32_bf16 v[100:103], v[146:149], v[202:205], v[100:103]
	v_mfma_f32_16x16x32_bf16 v[92:95], v[162:165], v[202:205], v[92:95]
	v_mfma_f32_16x16x32_bf16 v[84:87], v[146:149], v[210:213], v[84:87]
	v_mfma_f32_16x16x32_bf16 v[76:79], v[162:165], v[210:213], v[76:79]
	v_mfma_f32_16x16x32_bf16 v[124:127], v[158:161], v[190:193], v[124:127]
	v_mfma_f32_16x16x32_bf16 v[120:123], v[166:169], v[190:193], v[120:123]
	v_mfma_f32_16x16x32_bf16 v[116:119], v[158:161], v[198:201], v[116:119]
	v_mfma_f32_16x16x32_bf16 v[108:111], v[166:169], v[198:201], v[108:111]
	v_mfma_f32_16x16x32_bf16 v[100:103], v[158:161], v[206:209], v[100:103]
	v_mfma_f32_16x16x32_bf16 v[92:95], v[166:169], v[206:209], v[92:95]
	v_mfma_f32_16x16x32_bf16 v[84:87], v[158:161], v[214:217], v[84:87]
	v_mfma_f32_16x16x32_bf16 v[76:79], v[166:169], v[214:217], v[76:79]
	v_mfma_f32_16x16x32_bf16 v[112:115], v[170:173], v[186:189], v[112:115]
	v_mfma_f32_16x16x32_bf16 v[104:107], v[178:181], v[186:189], v[104:107]
	v_mfma_f32_16x16x32_bf16 v[96:99], v[170:173], v[194:197], v[96:99]
	v_mfma_f32_16x16x32_bf16 v[88:91], v[178:181], v[194:197], v[88:91]
	v_mfma_f32_16x16x32_bf16 v[80:83], v[170:173], v[202:205], v[80:83]
	v_mfma_f32_16x16x32_bf16 v[72:75], v[178:181], v[202:205], v[72:75]
	v_mfma_f32_16x16x32_bf16 v[68:71], v[170:173], v[210:213], v[68:71]
	v_mfma_f32_16x16x32_bf16 v[64:67], v[178:181], v[210:213], v[64:67]
	v_mfma_f32_16x16x32_bf16 v[112:115], v[174:177], v[190:193], v[112:115]
	v_mfma_f32_16x16x32_bf16 v[104:107], v[182:185], v[190:193], v[104:107]
	v_mfma_f32_16x16x32_bf16 v[96:99], v[174:177], v[198:201], v[96:99]
	v_mfma_f32_16x16x32_bf16 v[88:91], v[182:185], v[198:201], v[88:91]
	v_mfma_f32_16x16x32_bf16 v[80:83], v[174:177], v[206:209], v[80:83]
	v_mfma_f32_16x16x32_bf16 v[72:75], v[182:185], v[206:209], v[72:75]
	v_mfma_f32_16x16x32_bf16 v[68:71], v[174:177], v[214:217], v[68:71]
	v_mfma_f32_16x16x32_bf16 v[64:67], v[182:185], v[214:217], v[64:67]
	s_barrier
	s_setprio 0
	s_add_i32 s52, s52, s57
	v_lshl_add_u64 v[150:151], v[150:151], 0, s[8:9]
	s_mov_b32 m0, s52
	ds_read_b128 v[186:189], v157 offset:49152
	ds_read_b128 v[190:193], v157 offset:50176
	ds_read_b128 v[194:197], v157 offset:51200
	ds_read_b128 v[198:201], v157 offset:52224
	ds_read_b128 v[202:205], v157 offset:53248
	ds_read_b128 v[206:209], v157 offset:54272
	ds_read_b128 v[210:213], v157 offset:55296
	ds_read_b128 v[214:217], v157 offset:56320
	global_load_lds_dwordx4 v[150:151], off
	s_add_i32 m0, s52, 0x2000
	s_add_u32 s28, s28, 0x100080
	v_lshl_add_u64 v[150:151], v[218:219], 0, s[8:9]
	s_addc_u32 s29, s29, 0
	s_add_i32 s52, s53, s57
	global_load_lds_dwordx4 v[150:151], off
	v_lshl_add_u64 v[150:151], s[28:29], 0, v[132:133]
	s_mov_b32 m0, s52
	s_nop 0
	global_load_lds_dwordx4 v[150:151], off
	v_lshl_add_u64 v[150:151], s[28:29], 0, v[128:129]
	s_add_i32 m0, s52, 0x2000
	s_nop 0
	global_load_lds_dwordx4 v[150:151], off
	v_lshl_add_u64 v[150:151], v[220:221], 0, s[8:9]
	s_mov_b32 m0, s79
	s_nop 0
	global_load_lds_dwordx4 v[150:151], off
	v_lshl_add_u64 v[150:151], v[222:223], 0, s[8:9]
	s_mov_b32 m0, s80
	s_nop 0
	global_load_lds_dwordx4 v[150:151], off
	s_waitcnt vmcnt(8)
	s_waitcnt lgkmcnt(0)
	s_setprio 1
	s_barrier
	v_mfma_f32_16x16x32_bf16 v[60:63], v[146:149], v[186:189], v[60:63]
	v_mfma_f32_16x16x32_bf16 v[56:59], v[162:165], v[186:189], v[56:59]
	v_mfma_f32_16x16x32_bf16 v[52:55], v[146:149], v[194:197], v[52:55]
	v_mfma_f32_16x16x32_bf16 v[44:47], v[162:165], v[194:197], v[44:47]
	v_mfma_f32_16x16x32_bf16 v[36:39], v[146:149], v[202:205], v[36:39]
	v_mfma_f32_16x16x32_bf16 v[28:31], v[162:165], v[202:205], v[28:31]
	v_mfma_f32_16x16x32_bf16 v[20:23], v[146:149], v[210:213], v[20:23]
	v_mfma_f32_16x16x32_bf16 v[12:15], v[162:165], v[210:213], v[12:15]
	v_mfma_f32_16x16x32_bf16 v[60:63], v[158:161], v[190:193], v[60:63]
	v_mfma_f32_16x16x32_bf16 v[56:59], v[166:169], v[190:193], v[56:59]
	v_mfma_f32_16x16x32_bf16 v[52:55], v[158:161], v[198:201], v[52:55]
	v_mfma_f32_16x16x32_bf16 v[44:47], v[166:169], v[198:201], v[44:47]
	v_mfma_f32_16x16x32_bf16 v[36:39], v[158:161], v[206:209], v[36:39]
	v_mfma_f32_16x16x32_bf16 v[28:31], v[166:169], v[206:209], v[28:31]
	v_mfma_f32_16x16x32_bf16 v[20:23], v[158:161], v[214:217], v[20:23]
	v_mfma_f32_16x16x32_bf16 v[12:15], v[166:169], v[214:217], v[12:15]
	v_mfma_f32_16x16x32_bf16 v[48:51], v[170:173], v[186:189], v[48:51]
	v_mfma_f32_16x16x32_bf16 v[40:43], v[178:181], v[186:189], v[40:43]
	v_mfma_f32_16x16x32_bf16 v[32:35], v[170:173], v[194:197], v[32:35]
	v_mfma_f32_16x16x32_bf16 v[24:27], v[178:181], v[194:197], v[24:27]
	v_mfma_f32_16x16x32_bf16 v[16:19], v[170:173], v[202:205], v[16:19]
	v_mfma_f32_16x16x32_bf16 v[8:11], v[178:181], v[202:205], v[8:11]
	v_mfma_f32_16x16x32_bf16 v[4:7], v[170:173], v[210:213], v[4:7]
	v_mfma_f32_16x16x32_bf16 v[0:3], v[178:181], v[210:213], v[0:3]
	v_mfma_f32_16x16x32_bf16 v[48:51], v[174:177], v[190:193], v[48:51]
	v_mfma_f32_16x16x32_bf16 v[40:43], v[182:185], v[190:193], v[40:43]
	v_mfma_f32_16x16x32_bf16 v[32:35], v[174:177], v[198:201], v[32:35]
	v_mfma_f32_16x16x32_bf16 v[24:27], v[182:185], v[198:201], v[24:27]
	v_mfma_f32_16x16x32_bf16 v[16:19], v[174:177], v[206:209], v[16:19]
	v_mfma_f32_16x16x32_bf16 v[8:11], v[182:185], v[206:209], v[8:11]
	v_mfma_f32_16x16x32_bf16 v[4:7], v[174:177], v[214:217], v[4:7]
	v_mfma_f32_16x16x32_bf16 v[0:3], v[182:185], v[214:217], v[0:3]
	s_barrier
	s_setprio 0
	s_add_i32 s93, s93, 2
	s_add_u32 s70, s70, 0x100
	s_addc_u32 s71, s71, 0
	s_add_u32 s87, s87, 0x100
	s_addc_u32 s92, s92, 0
	s_cmp_gt_u32 s93, 61
	s_cbranch_scc0 .LBB8_266
	s_and_b64 vcc, exec, s[10:11]
	s_cbranch_vccnz .LBB8_271
	v_lshl_add_u32 v146, s68, 8, v152
	s_cmpk_gt_i32 s84, 0x4b
	s_mov_b64 s[28:29], -1
	s_cbranch_scc1 .LBB8_272

.LBB8_844:
	ds_read_b128 v[48:51], v229
	ds_read_b128 v[60:63], v229 offset:1024
	ds_read_b128 v[72:75], v229 offset:2048
	ds_read_b128 v[80:83], v229 offset:3072
	ds_read_b128 v[88:91], v230
	ds_read_b128 v[100:103], v230 offset:1024
	ds_read_b128 v[112:115], v230 offset:2048
	ds_read_b128 v[124:127], v230 offset:3072
	s_add_u32 s28, s24, 0xfff80080
	s_addc_u32 s29, s25, -1
	s_cmp_eq_u32 s58, 28
	s_cselect_b32 s35, s5, s29
	s_cselect_b32 s34, s17, s28
	s_cselect_b32 s29, s15, s57
	s_cselect_b32 s28, s23, s56
	v_lshl_add_u64 v[208:209], s[24:25], 0, v[200:201]
	s_add_i32 m0, s38, 0xc000
	ds_read_b128 v[144:147], v231
	ds_read_b128 v[156:159], v231 offset:1024
	ds_read_b128 v[168:171], v231 offset:2048
	ds_read_b128 v[172:175], v231 offset:3072
	ds_read_b128 v[176:179], v231 offset:4096
	ds_read_b128 v[180:183], v231 offset:5120
	ds_read_b128 v[184:187], v231 offset:6144
	ds_read_b128 v[188:191], v231 offset:7168
	global_load_lds_dwordx4 v[208:209], off
	v_lshl_add_u64 v[208:209], s[24:25], 0, v[202:203]
	s_add_i32 m0, s38, 0xe000
	s_nop 0
	global_load_lds_dwordx4 v[208:209], off
	s_waitcnt vmcnt(8)
	s_waitcnt lgkmcnt(0)
	s_setprio 1
	s_barrier
	v_mfma_f32_16x16x32_bf16 v[164:167], v[48:51], v[144:147], v[164:167]
	v_mfma_f32_16x16x32_bf16 v[160:163], v[72:75], v[144:147], v[160:163]
	v_mfma_f32_16x16x32_bf16 v[140:143], v[48:51], v[168:171], v[140:143]
	v_mfma_f32_16x16x32_bf16 v[136:139], v[72:75], v[168:171], v[136:139]
	v_mfma_f32_16x16x32_bf16 v[120:123], v[48:51], v[176:179], v[120:123]
	v_mfma_f32_16x16x32_bf16 v[116:119], v[72:75], v[176:179], v[116:119]
	v_mfma_f32_16x16x32_bf16 v[96:99], v[48:51], v[184:187], v[96:99]
	v_mfma_f32_16x16x32_bf16 v[92:95], v[72:75], v[184:187], v[92:95]
	v_mfma_f32_16x16x32_bf16 v[164:167], v[60:63], v[156:159], v[164:167]
	v_mfma_f32_16x16x32_bf16 v[160:163], v[80:83], v[156:159], v[160:163]
	v_mfma_f32_16x16x32_bf16 v[140:143], v[60:63], v[172:175], v[140:143]
	v_mfma_f32_16x16x32_bf16 v[136:139], v[80:83], v[172:175], v[136:139]
	v_mfma_f32_16x16x32_bf16 v[120:123], v[60:63], v[180:183], v[120:123]
	v_mfma_f32_16x16x32_bf16 v[116:119], v[80:83], v[180:183], v[116:119]
	v_mfma_f32_16x16x32_bf16 v[96:99], v[60:63], v[188:191], v[96:99]
	v_mfma_f32_16x16x32_bf16 v[92:95], v[80:83], v[188:191], v[92:95]
	v_mfma_f32_16x16x32_bf16 v[152:155], v[88:91], v[144:147], v[152:155]
	v_mfma_f32_16x16x32_bf16 v[132:135], v[88:91], v[168:171], v[132:135]
	v_mfma_f32_16x16x32_bf16 v[128:131], v[112:115], v[168:171], v[128:131]
	v_mfma_f32_16x16x32_bf16 v[108:111], v[88:91], v[176:179], v[108:111]
	v_mfma_f32_16x16x32_bf16 v[104:107], v[112:115], v[176:179], v[104:107]
	v_mfma_f32_16x16x32_bf16 v[84:87], v[88:91], v[184:187], v[84:87]
	v_mfma_f32_16x16x32_bf16 v[76:79], v[112:115], v[184:187], v[76:79]
	v_mfma_f32_16x16x32_bf16 v[152:155], v[100:103], v[156:159], v[152:155]
	v_mfma_f32_16x16x32_bf16 v[144:147], v[112:115], v[144:147], v[148:151]
	v_mfma_f32_16x16x32_bf16 v[132:135], v[100:103], v[172:175], v[132:135]
	v_mfma_f32_16x16x32_bf16 v[128:131], v[124:127], v[172:175], v[128:131]
	v_mfma_f32_16x16x32_bf16 v[108:111], v[100:103], v[180:183], v[108:111]
	v_mfma_f32_16x16x32_bf16 v[104:107], v[124:127], v[180:183], v[104:107]
	v_mfma_f32_16x16x32_bf16 v[84:87], v[100:103], v[188:191], v[84:87]
	v_mfma_f32_16x16x32_bf16 v[76:79], v[124:127], v[188:191], v[76:79]
	v_mfma_f32_16x16x32_bf16 v[144:147], v[124:127], v[156:159], v[144:147]
	s_barrier
	s_setprio 0
	s_add_i32 s52, s46, s33
	v_lshl_add_u64 v[208:209], s[28:29], 0, v[194:195]
	s_mov_b32 m0, s52
	ds_read_b128 v[148:151], v231 offset:16384
	ds_read_b128 v[156:159], v231 offset:17408
	ds_read_b128 v[168:171], v231 offset:18432
	ds_read_b128 v[172:175], v231 offset:19456
	ds_read_b128 v[176:179], v231 offset:20480
	ds_read_b128 v[180:183], v231 offset:21504
	ds_read_b128 v[184:187], v231 offset:22528
	ds_read_b128 v[188:191], v231 offset:23552
	global_load_lds_dwordx4 v[208:209], off
	s_add_i32 m0, s52, 0x2000
	s_add_u32 s52, s28, 0x80000
	v_lshl_add_u64 v[210:211], s[28:29], 0, v[198:199]
	s_addc_u32 s53, s29, 0
	s_add_i32 s59, s47, s33
	global_load_lds_dwordx4 v[210:211], off
	v_lshl_add_u64 v[212:213], s[52:53], 0, v[194:195]
	s_mov_b32 m0, s59
	v_lshl_add_u64 v[214:215], s[34:35], 0, v[196:197]
	global_load_lds_dwordx4 v[212:213], off
	v_lshl_add_u64 v[212:213], s[52:53], 0, v[198:199]
	s_add_i32 m0, s59, 0x2000
	s_nop 0
	global_load_lds_dwordx4 v[212:213], off
	v_lshl_add_u64 v[212:213], s[34:35], 0, v[192:193]
	s_mov_b32 m0, s38
	s_nop 0
	global_load_lds_dwordx4 v[212:213], off
	s_mov_b32 m0, s39
	s_nop 0
	global_load_lds_dwordx4 v[214:215], off
	s_waitcnt vmcnt(8)
	s_waitcnt lgkmcnt(0)
	s_setprio 1
	s_barrier
	v_mfma_f32_16x16x32_bf16 v[68:71], v[48:51], v[148:151], v[68:71]
	v_mfma_f32_16x16x32_bf16 v[64:67], v[72:75], v[148:151], v[64:67]
	v_mfma_f32_16x16x32_bf16 v[44:47], v[48:51], v[168:171], v[44:47]
	v_mfma_f32_16x16x32_bf16 v[40:43], v[72:75], v[168:171], v[40:43]
	v_mfma_f32_16x16x32_bf16 v[28:31], v[48:51], v[176:179], v[28:31]
	v_mfma_f32_16x16x32_bf16 v[24:27], v[72:75], v[176:179], v[24:27]
	v_mfma_f32_16x16x32_bf16 v[12:15], v[48:51], v[184:187], v[12:15]
	v_mfma_f32_16x16x32_bf16 v[8:11], v[72:75], v[184:187], v[8:11]
	v_mfma_f32_16x16x32_bf16 v[68:71], v[60:63], v[156:159], v[68:71]
	v_mfma_f32_16x16x32_bf16 v[64:67], v[80:83], v[156:159], v[64:67]
	v_mfma_f32_16x16x32_bf16 v[44:47], v[60:63], v[172:175], v[44:47]
	v_mfma_f32_16x16x32_bf16 v[40:43], v[80:83], v[172:175], v[40:43]
	v_mfma_f32_16x16x32_bf16 v[28:31], v[60:63], v[180:183], v[28:31]
	v_mfma_f32_16x16x32_bf16 v[24:27], v[80:83], v[180:183], v[24:27]
	v_mfma_f32_16x16x32_bf16 v[12:15], v[60:63], v[188:191], v[12:15]
	v_mfma_f32_16x16x32_bf16 v[8:11], v[80:83], v[188:191], v[8:11]
	v_mfma_f32_16x16x32_bf16 v[52:55], v[112:115], v[148:151], v[52:55]
	v_mfma_f32_16x16x32_bf16 v[36:39], v[88:91], v[168:171], v[36:39]
	v_mfma_f32_16x16x32_bf16 v[32:35], v[112:115], v[168:171], v[32:35]
	v_mfma_f32_16x16x32_bf16 v[20:23], v[88:91], v[176:179], v[20:23]
	v_mfma_f32_16x16x32_bf16 v[16:19], v[112:115], v[176:179], v[16:19]
	v_mfma_f32_16x16x32_bf16 v[4:7], v[88:91], v[184:187], v[4:7]
	v_mfma_f32_16x16x32_bf16 v[0:3], v[112:115], v[184:187], v[0:3]
	v_mfma_f32_16x16x32_bf16 v[48:51], v[88:91], v[148:151], v[56:59]
	v_mfma_f32_16x16x32_bf16 v[52:55], v[124:127], v[156:159], v[52:55]
	v_mfma_f32_16x16x32_bf16 v[36:39], v[100:103], v[172:175], v[36:39]
	v_mfma_f32_16x16x32_bf16 v[32:35], v[124:127], v[172:175], v[32:35]
	v_mfma_f32_16x16x32_bf16 v[20:23], v[100:103], v[180:183], v[20:23]
	v_mfma_f32_16x16x32_bf16 v[16:19], v[124:127], v[180:183], v[16:19]
	v_mfma_f32_16x16x32_bf16 v[4:7], v[100:103], v[188:191], v[4:7]
	v_mfma_f32_16x16x32_bf16 v[0:3], v[124:127], v[188:191], v[0:3]
	v_mfma_f32_16x16x32_bf16 v[48:51], v[100:103], v[156:159], v[48:51]
	s_barrier
	s_setprio 0
	s_add_i32 s52, 0, 0x18000
	s_add_i32 s53, 0, 0x1c000
	v_add_u32_e32 v80, s52, v227
	v_add_u32_e32 v124, s53, v227
	ds_read_b128 v[56:59], v80
	ds_read_b128 v[60:63], v80 offset:1024
	ds_read_b128 v[72:75], v80 offset:2048
	ds_read_b128 v[80:83], v80 offset:3072
	ds_read_b128 v[88:91], v124
	ds_read_b128 v[100:103], v124 offset:1024
	ds_read_b128 v[112:115], v124 offset:2048
	ds_read_b128 v[124:127], v124 offset:3072
	s_add_u32 s34, s34, 0x80000
	s_addc_u32 s35, s35, 0
	s_mov_b32 m0, s40
	v_lshl_add_u64 v[216:217], s[34:35], 0, v[192:193]
	ds_read_b128 v[148:151], v231 offset:32768
	ds_read_b128 v[156:159], v231 offset:33792
	ds_read_b128 v[168:171], v231 offset:34816
	ds_read_b128 v[172:175], v231 offset:35840
	ds_read_b128 v[176:179], v231 offset:36864
	ds_read_b128 v[180:183], v231 offset:37888
	ds_read_b128 v[184:187], v231 offset:38912
	ds_read_b128 v[188:191], v231 offset:39936
	global_load_lds_dwordx4 v[216:217], off
	v_lshl_add_u64 v[216:217], s[34:35], 0, v[196:197]
	s_mov_b32 m0, s41
	s_nop 0
	global_load_lds_dwordx4 v[216:217], off
	s_waitcnt vmcnt(8)
	s_waitcnt lgkmcnt(0)
	s_setprio 1
	s_barrier
	v_mfma_f32_16x16x32_bf16 v[164:167], v[56:59], v[148:151], v[164:167]
	v_mfma_f32_16x16x32_bf16 v[160:163], v[72:75], v[148:151], v[160:163]
	v_mfma_f32_16x16x32_bf16 v[140:143], v[56:59], v[168:171], v[140:143]
	v_mfma_f32_16x16x32_bf16 v[136:139], v[72:75], v[168:171], v[136:139]
	v_mfma_f32_16x16x32_bf16 v[120:123], v[56:59], v[176:179], v[120:123]
	v_mfma_f32_16x16x32_bf16 v[116:119], v[72:75], v[176:179], v[116:119]
	v_mfma_f32_16x16x32_bf16 v[96:99], v[56:59], v[184:187], v[96:99]
	v_mfma_f32_16x16x32_bf16 v[92:95], v[72:75], v[184:187], v[92:95]
	v_mfma_f32_16x16x32_bf16 v[164:167], v[60:63], v[156:159], v[164:167]
	v_mfma_f32_16x16x32_bf16 v[160:163], v[80:83], v[156:159], v[160:163]
	v_mfma_f32_16x16x32_bf16 v[140:143], v[60:63], v[172:175], v[140:143]
	v_mfma_f32_16x16x32_bf16 v[136:139], v[80:83], v[172:175], v[136:139]
	v_mfma_f32_16x16x32_bf16 v[120:123], v[60:63], v[180:183], v[120:123]
	v_mfma_f32_16x16x32_bf16 v[116:119], v[80:83], v[180:183], v[116:119]
	v_mfma_f32_16x16x32_bf16 v[96:99], v[60:63], v[188:191], v[96:99]
	v_mfma_f32_16x16x32_bf16 v[92:95], v[80:83], v[188:191], v[92:95]
	v_mfma_f32_16x16x32_bf16 v[152:155], v[88:91], v[148:151], v[152:155]
	v_mfma_f32_16x16x32_bf16 v[144:147], v[112:115], v[148:151], v[144:147]
	v_mfma_f32_16x16x32_bf16 v[132:135], v[88:91], v[168:171], v[132:135]
	v_mfma_f32_16x16x32_bf16 v[128:131], v[112:115], v[168:171], v[128:131]
	v_mfma_f32_16x16x32_bf16 v[108:111], v[88:91], v[176:179], v[108:111]
	v_mfma_f32_16x16x32_bf16 v[104:107], v[112:115], v[176:179], v[104:107]
	v_mfma_f32_16x16x32_bf16 v[84:87], v[88:91], v[184:187], v[84:87]
	v_mfma_f32_16x16x32_bf16 v[76:79], v[112:115], v[184:187], v[76:79]
	v_mfma_f32_16x16x32_bf16 v[152:155], v[100:103], v[156:159], v[152:155]
	v_mfma_f32_16x16x32_bf16 v[148:151], v[124:127], v[156:159], v[144:147]
	v_mfma_f32_16x16x32_bf16 v[132:135], v[100:103], v[172:175], v[132:135]
	v_mfma_f32_16x16x32_bf16 v[128:131], v[124:127], v[172:175], v[128:131]
	v_mfma_f32_16x16x32_bf16 v[108:111], v[100:103], v[180:183], v[108:111]
	v_mfma_f32_16x16x32_bf16 v[104:107], v[124:127], v[180:183], v[104:107]
	v_mfma_f32_16x16x32_bf16 v[84:87], v[100:103], v[188:191], v[84:87]
	v_mfma_f32_16x16x32_bf16 v[76:79], v[124:127], v[188:191], v[76:79]
	s_barrier
	s_setprio 0
	s_add_i32 s34, s52, s33
	v_lshl_add_u64 v[208:209], v[208:209], 0, s[10:11]
	s_mov_b32 m0, s34
	ds_read_b128 v[144:147], v231 offset:49152
	ds_read_b128 v[156:159], v231 offset:50176
	ds_read_b128 v[168:171], v231 offset:51200
	ds_read_b128 v[172:175], v231 offset:52224
	ds_read_b128 v[176:179], v231 offset:53248
	ds_read_b128 v[180:183], v231 offset:54272
	ds_read_b128 v[184:187], v231 offset:55296
	ds_read_b128 v[188:191], v231 offset:56320
	global_load_lds_dwordx4 v[208:209], off
	s_add_i32 m0, s34, 0x2000
	s_add_u32 s28, s28, 0x80080
	v_lshl_add_u64 v[208:209], v[210:211], 0, s[10:11]
	s_addc_u32 s29, s29, 0
	s_add_i32 s34, s53, s33
	global_load_lds_dwordx4 v[208:209], off
	v_lshl_add_u64 v[208:209], s[28:29], 0, v[194:195]
	s_mov_b32 m0, s34
	s_nop 0
	global_load_lds_dwordx4 v[208:209], off
	v_lshl_add_u64 v[208:209], s[28:29], 0, v[198:199]
	s_add_i32 m0, s34, 0x2000
	s_nop 0
	global_load_lds_dwordx4 v[208:209], off
	v_lshl_add_u64 v[208:209], v[212:213], 0, s[10:11]
	s_mov_b32 m0, s44
	s_nop 0
	global_load_lds_dwordx4 v[208:209], off
	v_lshl_add_u64 v[208:209], v[214:215], 0, s[10:11]
	s_mov_b32 m0, s45
	s_nop 0
	global_load_lds_dwordx4 v[208:209], off
	s_waitcnt vmcnt(8)
	s_waitcnt lgkmcnt(0)
	s_setprio 1
	s_barrier
	v_mfma_f32_16x16x32_bf16 v[68:71], v[56:59], v[144:147], v[68:71]
	v_mfma_f32_16x16x32_bf16 v[64:67], v[72:75], v[144:147], v[64:67]
	v_mfma_f32_16x16x32_bf16 v[44:47], v[56:59], v[168:171], v[44:47]
	v_mfma_f32_16x16x32_bf16 v[40:43], v[72:75], v[168:171], v[40:43]
	v_mfma_f32_16x16x32_bf16 v[28:31], v[56:59], v[176:179], v[28:31]
	v_mfma_f32_16x16x32_bf16 v[24:27], v[72:75], v[176:179], v[24:27]
	v_mfma_f32_16x16x32_bf16 v[12:15], v[56:59], v[184:187], v[12:15]
	v_mfma_f32_16x16x32_bf16 v[8:11], v[72:75], v[184:187], v[8:11]
	v_mfma_f32_16x16x32_bf16 v[68:71], v[60:63], v[156:159], v[68:71]
	v_mfma_f32_16x16x32_bf16 v[64:67], v[80:83], v[156:159], v[64:67]
	v_mfma_f32_16x16x32_bf16 v[44:47], v[60:63], v[172:175], v[44:47]
	v_mfma_f32_16x16x32_bf16 v[40:43], v[80:83], v[172:175], v[40:43]
	v_mfma_f32_16x16x32_bf16 v[28:31], v[60:63], v[180:183], v[28:31]
	v_mfma_f32_16x16x32_bf16 v[24:27], v[80:83], v[180:183], v[24:27]
	v_mfma_f32_16x16x32_bf16 v[12:15], v[60:63], v[188:191], v[12:15]
	v_mfma_f32_16x16x32_bf16 v[8:11], v[80:83], v[188:191], v[8:11]
	v_mfma_f32_16x16x32_bf16 v[48:51], v[88:91], v[144:147], v[48:51]
	v_mfma_f32_16x16x32_bf16 v[56:59], v[100:103], v[156:159], v[48:51]
	v_mfma_f32_16x16x32_bf16 v[48:51], v[112:115], v[144:147], v[52:55]
	v_mfma_f32_16x16x32_bf16 v[36:39], v[88:91], v[168:171], v[36:39]
	v_mfma_f32_16x16x32_bf16 v[32:35], v[112:115], v[168:171], v[32:35]
	v_mfma_f32_16x16x32_bf16 v[20:23], v[88:91], v[176:179], v[20:23]
	v_mfma_f32_16x16x32_bf16 v[16:19], v[112:115], v[176:179], v[16:19]
	v_mfma_f32_16x16x32_bf16 v[4:7], v[88:91], v[184:187], v[4:7]
	v_mfma_f32_16x16x32_bf16 v[0:3], v[112:115], v[184:187], v[0:3]
	v_mfma_f32_16x16x32_bf16 v[52:55], v[124:127], v[156:159], v[48:51]
	v_mfma_f32_16x16x32_bf16 v[36:39], v[100:103], v[172:175], v[36:39]
	v_mfma_f32_16x16x32_bf16 v[32:35], v[124:127], v[172:175], v[32:35]
	v_mfma_f32_16x16x32_bf16 v[20:23], v[100:103], v[180:183], v[20:23]
	v_mfma_f32_16x16x32_bf16 v[16:19], v[124:127], v[180:183], v[16:19]
	v_mfma_f32_16x16x32_bf16 v[4:7], v[100:103], v[188:191], v[4:7]
	v_mfma_f32_16x16x32_bf16 v[0:3], v[124:127], v[188:191], v[0:3]
	s_barrier
	s_setprio 0
	s_add_i32 s58, s58, 2
	s_add_u32 s24, s24, 0x100
	s_addc_u32 s25, s25, 0
	s_add_u32 s56, s56, 0x100
	s_addc_u32 s57, s57, 0
	s_cmp_gt_u32 s58, 29
	s_cbranch_scc0 .LBB8_844
	s_and_b64 vcc, exec, s[12:13]
	s_cbranch_vccz .LBB8_847
	s_barrier

.LBB8_961:
	ds_read_b128 v[76:79], v191
	ds_read_b128 v[84:87], v191 offset:1024
	ds_read_b128 v[88:91], v191 offset:2048
	ds_read_b128 v[96:99], v191 offset:3072
	ds_read_b128 v[144:147], v192
	ds_read_b128 v[148:151], v192 offset:1024
	ds_read_b128 v[152:155], v192 offset:2048
	ds_read_b128 v[156:159], v192 offset:3072
	s_add_u32 s28, s40, 0xfff00080
	s_addc_u32 s29, s41, -1
	s_cmp_eq_u32 s69, 60
	s_cselect_b32 s43, s19, s29
	s_cselect_b32 s42, s25, s28
	s_cselect_b32 s29, s17, s68
	s_cselect_b32 s28, s66, s67
	v_lshl_add_u64 v[216:217], s[40:41], 0, v[168:169]
	s_add_i32 m0, s35, 0xc000
	ds_read_b128 v[176:179], v193
	ds_read_b128 v[180:183], v193 offset:1024
	ds_read_b128 v[184:187], v193 offset:2048
	ds_read_b128 v[196:199], v193 offset:3072
	ds_read_b128 v[200:203], v193 offset:4096
	ds_read_b128 v[204:207], v193 offset:5120
	ds_read_b128 v[208:211], v193 offset:6144
	ds_read_b128 v[212:215], v193 offset:7168
	global_load_lds_dwordx4 v[216:217], off
	v_lshl_add_u64 v[216:217], s[40:41], 0, v[170:171]
	s_add_i32 m0, s35, 0xe000
	s_nop 0
	global_load_lds_dwordx4 v[216:217], off
	s_waitcnt vmcnt(8)
	s_waitcnt lgkmcnt(0)
	s_setprio 1
	s_barrier
	v_mfma_f32_16x16x32_bf16 v[140:143], v[76:79], v[176:179], v[140:143]
	v_mfma_f32_16x16x32_bf16 v[136:139], v[88:91], v[176:179], v[136:139]
	v_mfma_f32_16x16x32_bf16 v[124:127], v[76:79], v[184:187], v[124:127]
	v_mfma_f32_16x16x32_bf16 v[120:123], v[88:91], v[184:187], v[120:123]
	v_mfma_f32_16x16x32_bf16 v[108:111], v[76:79], v[200:203], v[108:111]
	v_mfma_f32_16x16x32_bf16 v[104:107], v[88:91], v[200:203], v[104:107]
	v_mfma_f32_16x16x32_bf16 v[80:83], v[76:79], v[208:211], v[80:83]
	v_mfma_f32_16x16x32_bf16 v[72:75], v[88:91], v[208:211], v[72:75]
	v_mfma_f32_16x16x32_bf16 v[140:143], v[84:87], v[180:183], v[140:143]
	v_mfma_f32_16x16x32_bf16 v[136:139], v[96:99], v[180:183], v[136:139]
	v_mfma_f32_16x16x32_bf16 v[124:127], v[84:87], v[196:199], v[124:127]
	v_mfma_f32_16x16x32_bf16 v[120:123], v[96:99], v[196:199], v[120:123]
	v_mfma_f32_16x16x32_bf16 v[108:111], v[84:87], v[204:207], v[108:111]
	v_mfma_f32_16x16x32_bf16 v[104:107], v[96:99], v[204:207], v[104:107]
	v_mfma_f32_16x16x32_bf16 v[80:83], v[84:87], v[212:215], v[80:83]
	v_mfma_f32_16x16x32_bf16 v[72:75], v[96:99], v[212:215], v[72:75]
	v_mfma_f32_16x16x32_bf16 v[132:135], v[144:147], v[176:179], v[132:135]
	v_mfma_f32_16x16x32_bf16 v[128:131], v[152:155], v[176:179], v[128:131]
	v_mfma_f32_16x16x32_bf16 v[116:119], v[144:147], v[184:187], v[116:119]
	v_mfma_f32_16x16x32_bf16 v[112:115], v[152:155], v[184:187], v[112:115]
	v_mfma_f32_16x16x32_bf16 v[100:103], v[144:147], v[200:203], v[100:103]
	v_mfma_f32_16x16x32_bf16 v[92:95], v[152:155], v[200:203], v[92:95]
	v_mfma_f32_16x16x32_bf16 v[68:71], v[144:147], v[208:211], v[68:71]
	v_mfma_f32_16x16x32_bf16 v[64:67], v[152:155], v[208:211], v[64:67]
	v_mfma_f32_16x16x32_bf16 v[132:135], v[148:151], v[180:183], v[132:135]
	v_mfma_f32_16x16x32_bf16 v[128:131], v[156:159], v[180:183], v[128:131]
	v_mfma_f32_16x16x32_bf16 v[116:119], v[148:151], v[196:199], v[116:119]
	v_mfma_f32_16x16x32_bf16 v[112:115], v[156:159], v[196:199], v[112:115]
	v_mfma_f32_16x16x32_bf16 v[100:103], v[148:151], v[204:207], v[100:103]
	v_mfma_f32_16x16x32_bf16 v[92:95], v[156:159], v[204:207], v[92:95]
	v_mfma_f32_16x16x32_bf16 v[68:71], v[148:151], v[212:215], v[68:71]
	v_mfma_f32_16x16x32_bf16 v[64:67], v[156:159], v[212:215], v[64:67]
	s_barrier
	s_setprio 0
	s_add_i32 s52, s60, s33
	v_lshl_add_u64 v[216:217], s[28:29], 0, v[162:163]
	s_mov_b32 m0, s52
	ds_read_b128 v[176:179], v193 offset:16384
	ds_read_b128 v[180:183], v193 offset:17408
	ds_read_b128 v[184:187], v193 offset:18432
	ds_read_b128 v[196:199], v193 offset:19456
	ds_read_b128 v[200:203], v193 offset:20480
	ds_read_b128 v[204:207], v193 offset:21504
	ds_read_b128 v[208:211], v193 offset:22528
	ds_read_b128 v[212:215], v193 offset:23552
	global_load_lds_dwordx4 v[216:217], off
	s_add_i32 m0, s52, 0x2000
	s_add_u32 s52, s28, 0x100000
	v_lshl_add_u64 v[218:219], s[28:29], 0, v[166:167]
	s_addc_u32 s53, s29, 0
	s_add_i32 s62, s61, s33
	global_load_lds_dwordx4 v[218:219], off
	v_lshl_add_u64 v[220:221], s[52:53], 0, v[162:163]
	s_mov_b32 m0, s62
	v_lshl_add_u64 v[222:223], s[42:43], 0, v[164:165]
	global_load_lds_dwordx4 v[220:221], off
	v_lshl_add_u64 v[220:221], s[52:53], 0, v[166:167]
	s_add_i32 m0, s62, 0x2000
	s_nop 0
	global_load_lds_dwordx4 v[220:221], off
	v_lshl_add_u64 v[220:221], s[42:43], 0, v[160:161]
	s_mov_b32 m0, s35
	s_nop 0
	global_load_lds_dwordx4 v[220:221], off
	s_mov_b32 m0, s38
	s_nop 0
	global_load_lds_dwordx4 v[222:223], off
	s_waitcnt vmcnt(8)
	s_waitcnt lgkmcnt(0)
	s_setprio 1
	s_barrier
	v_mfma_f32_16x16x32_bf16 v[60:63], v[76:79], v[176:179], v[60:63]
	v_mfma_f32_16x16x32_bf16 v[56:59], v[88:91], v[176:179], v[56:59]
	v_mfma_f32_16x16x32_bf16 v[44:47], v[76:79], v[184:187], v[44:47]
	v_mfma_f32_16x16x32_bf16 v[40:43], v[88:91], v[184:187], v[40:43]
	v_mfma_f32_16x16x32_bf16 v[28:31], v[76:79], v[200:203], v[28:31]
	v_mfma_f32_16x16x32_bf16 v[24:27], v[88:91], v[200:203], v[24:27]
	v_mfma_f32_16x16x32_bf16 v[12:15], v[76:79], v[208:211], v[12:15]
	v_mfma_f32_16x16x32_bf16 v[8:11], v[88:91], v[208:211], v[8:11]
	v_mfma_f32_16x16x32_bf16 v[60:63], v[84:87], v[180:183], v[60:63]
	v_mfma_f32_16x16x32_bf16 v[56:59], v[96:99], v[180:183], v[56:59]
	v_mfma_f32_16x16x32_bf16 v[44:47], v[84:87], v[196:199], v[44:47]
	v_mfma_f32_16x16x32_bf16 v[40:43], v[96:99], v[196:199], v[40:43]
	v_mfma_f32_16x16x32_bf16 v[28:31], v[84:87], v[204:207], v[28:31]
	v_mfma_f32_16x16x32_bf16 v[24:27], v[96:99], v[204:207], v[24:27]
	v_mfma_f32_16x16x32_bf16 v[12:15], v[84:87], v[212:215], v[12:15]
	v_mfma_f32_16x16x32_bf16 v[8:11], v[96:99], v[212:215], v[8:11]
	v_mfma_f32_16x16x32_bf16 v[52:55], v[144:147], v[176:179], v[52:55]
	v_mfma_f32_16x16x32_bf16 v[48:51], v[152:155], v[176:179], v[48:51]
	v_mfma_f32_16x16x32_bf16 v[36:39], v[144:147], v[184:187], v[36:39]
	v_mfma_f32_16x16x32_bf16 v[32:35], v[152:155], v[184:187], v[32:35]
	v_mfma_f32_16x16x32_bf16 v[20:23], v[144:147], v[200:203], v[20:23]
	v_mfma_f32_16x16x32_bf16 v[16:19], v[152:155], v[200:203], v[16:19]
	v_mfma_f32_16x16x32_bf16 v[4:7], v[144:147], v[208:211], v[4:7]
	v_mfma_f32_16x16x32_bf16 v[0:3], v[152:155], v[208:211], v[0:3]
	v_mfma_f32_16x16x32_bf16 v[52:55], v[148:151], v[180:183], v[52:55]
	v_mfma_f32_16x16x32_bf16 v[48:51], v[156:159], v[180:183], v[48:51]
	v_mfma_f32_16x16x32_bf16 v[36:39], v[148:151], v[196:199], v[36:39]
	v_mfma_f32_16x16x32_bf16 v[32:35], v[156:159], v[196:199], v[32:35]
	v_mfma_f32_16x16x32_bf16 v[20:23], v[148:151], v[204:207], v[20:23]
	v_mfma_f32_16x16x32_bf16 v[16:19], v[156:159], v[204:207], v[16:19]
	v_mfma_f32_16x16x32_bf16 v[4:7], v[148:151], v[212:215], v[4:7]
	v_mfma_f32_16x16x32_bf16 v[0:3], v[156:159], v[212:215], v[0:3]
	s_barrier
	s_setprio 0
	s_add_i32 s52, 0, 0x18000
	s_add_i32 s53, 0, 0x1c000
	v_add_u32_e32 v96, s52, v189
	v_add_u32_e32 v156, s53, v189
	ds_read_b128 v[76:79], v96
	ds_read_b128 v[84:87], v96 offset:1024
	ds_read_b128 v[88:91], v96 offset:2048
	ds_read_b128 v[96:99], v96 offset:3072
	ds_read_b128 v[144:147], v156
	ds_read_b128 v[148:151], v156 offset:1024
	ds_read_b128 v[152:155], v156 offset:2048
	ds_read_b128 v[156:159], v156 offset:3072
	s_add_u32 s42, s42, 0x100000
	s_addc_u32 s43, s43, 0
	s_mov_b32 m0, s39
	v_lshl_add_u64 v[224:225], s[42:43], 0, v[160:161]
	ds_read_b128 v[176:179], v193 offset:32768
	ds_read_b128 v[180:183], v193 offset:33792
	ds_read_b128 v[184:187], v193 offset:34816
	ds_read_b128 v[196:199], v193 offset:35840
	ds_read_b128 v[200:203], v193 offset:36864
	ds_read_b128 v[204:207], v193 offset:37888
	ds_read_b128 v[208:211], v193 offset:38912
	ds_read_b128 v[212:215], v193 offset:39936
	global_load_lds_dwordx4 v[224:225], off
	v_lshl_add_u64 v[224:225], s[42:43], 0, v[164:165]
	s_mov_b32 m0, s44
	s_nop 0
	global_load_lds_dwordx4 v[224:225], off
	s_waitcnt vmcnt(8)
	s_waitcnt lgkmcnt(0)
	s_setprio 1
	s_barrier
	v_mfma_f32_16x16x32_bf16 v[140:143], v[76:79], v[176:179], v[140:143]
	v_mfma_f32_16x16x32_bf16 v[136:139], v[88:91], v[176:179], v[136:139]
	v_mfma_f32_16x16x32_bf16 v[124:127], v[76:79], v[184:187], v[124:127]
	v_mfma_f32_16x16x32_bf16 v[120:123], v[88:91], v[184:187], v[120:123]
	v_mfma_f32_16x16x32_bf16 v[108:111], v[76:79], v[200:203], v[108:111]
	v_mfma_f32_16x16x32_bf16 v[104:107], v[88:91], v[200:203], v[104:107]
	v_mfma_f32_16x16x32_bf16 v[80:83], v[76:79], v[208:211], v[80:83]
	v_mfma_f32_16x16x32_bf16 v[72:75], v[88:91], v[208:211], v[72:75]
	v_mfma_f32_16x16x32_bf16 v[140:143], v[84:87], v[180:183], v[140:143]
	v_mfma_f32_16x16x32_bf16 v[136:139], v[96:99], v[180:183], v[136:139]
	v_mfma_f32_16x16x32_bf16 v[124:127], v[84:87], v[196:199], v[124:127]
	v_mfma_f32_16x16x32_bf16 v[120:123], v[96:99], v[196:199], v[120:123]
	v_mfma_f32_16x16x32_bf16 v[108:111], v[84:87], v[204:207], v[108:111]
	v_mfma_f32_16x16x32_bf16 v[104:107], v[96:99], v[204:207], v[104:107]
	v_mfma_f32_16x16x32_bf16 v[80:83], v[84:87], v[212:215], v[80:83]
	v_mfma_f32_16x16x32_bf16 v[72:75], v[96:99], v[212:215], v[72:75]
	v_mfma_f32_16x16x32_bf16 v[132:135], v[144:147], v[176:179], v[132:135]
	v_mfma_f32_16x16x32_bf16 v[128:131], v[152:155], v[176:179], v[128:131]
	v_mfma_f32_16x16x32_bf16 v[116:119], v[144:147], v[184:187], v[116:119]
	v_mfma_f32_16x16x32_bf16 v[112:115], v[152:155], v[184:187], v[112:115]
	v_mfma_f32_16x16x32_bf16 v[100:103], v[144:147], v[200:203], v[100:103]
	v_mfma_f32_16x16x32_bf16 v[92:95], v[152:155], v[200:203], v[92:95]
	v_mfma_f32_16x16x32_bf16 v[68:71], v[144:147], v[208:211], v[68:71]
	v_mfma_f32_16x16x32_bf16 v[64:67], v[152:155], v[208:211], v[64:67]
	v_mfma_f32_16x16x32_bf16 v[132:135], v[148:151], v[180:183], v[132:135]
	v_mfma_f32_16x16x32_bf16 v[128:131], v[156:159], v[180:183], v[128:131]
	v_mfma_f32_16x16x32_bf16 v[116:119], v[148:151], v[196:199], v[116:119]
	v_mfma_f32_16x16x32_bf16 v[112:115], v[156:159], v[196:199], v[112:115]
	v_mfma_f32_16x16x32_bf16 v[100:103], v[148:151], v[204:207], v[100:103]
	v_mfma_f32_16x16x32_bf16 v[92:95], v[156:159], v[204:207], v[92:95]
	v_mfma_f32_16x16x32_bf16 v[68:71], v[148:151], v[212:215], v[68:71]
	v_mfma_f32_16x16x32_bf16 v[64:67], v[156:159], v[212:215], v[64:67]
	s_barrier
	s_setprio 0
	s_add_i32 s42, s52, s33
	v_lshl_add_u64 v[216:217], v[216:217], 0, s[12:13]
	s_mov_b32 m0, s42
	ds_read_b128 v[176:179], v193 offset:49152
	ds_read_b128 v[180:183], v193 offset:50176
	ds_read_b128 v[184:187], v193 offset:51200
	ds_read_b128 v[196:199], v193 offset:52224
	ds_read_b128 v[200:203], v193 offset:53248
	ds_read_b128 v[204:207], v193 offset:54272
	ds_read_b128 v[208:211], v193 offset:55296
	ds_read_b128 v[212:215], v193 offset:56320
	global_load_lds_dwordx4 v[216:217], off
	s_add_i32 m0, s42, 0x2000
	s_add_u32 s28, s28, 0x100080
	v_lshl_add_u64 v[216:217], v[218:219], 0, s[12:13]
	s_addc_u32 s29, s29, 0
	s_add_i32 s42, s53, s33
	global_load_lds_dwordx4 v[216:217], off
	v_lshl_add_u64 v[216:217], s[28:29], 0, v[162:163]
	s_mov_b32 m0, s42
	s_nop 0
	global_load_lds_dwordx4 v[216:217], off
	v_lshl_add_u64 v[216:217], s[28:29], 0, v[166:167]
	s_add_i32 m0, s42, 0x2000
	s_nop 0
	global_load_lds_dwordx4 v[216:217], off
	v_lshl_add_u64 v[216:217], v[220:221], 0, s[12:13]
	s_mov_b32 m0, s58
	s_nop 0
	global_load_lds_dwordx4 v[216:217], off
	v_lshl_add_u64 v[216:217], v[222:223], 0, s[12:13]
	s_mov_b32 m0, s59
	s_nop 0
	global_load_lds_dwordx4 v[216:217], off
	s_waitcnt vmcnt(8)
	s_waitcnt lgkmcnt(0)
	s_setprio 1
	s_barrier
	v_mfma_f32_16x16x32_bf16 v[60:63], v[76:79], v[176:179], v[60:63]
	v_mfma_f32_16x16x32_bf16 v[56:59], v[88:91], v[176:179], v[56:59]
	v_mfma_f32_16x16x32_bf16 v[44:47], v[76:79], v[184:187], v[44:47]
	v_mfma_f32_16x16x32_bf16 v[40:43], v[88:91], v[184:187], v[40:43]
	v_mfma_f32_16x16x32_bf16 v[28:31], v[76:79], v[200:203], v[28:31]
	v_mfma_f32_16x16x32_bf16 v[24:27], v[88:91], v[200:203], v[24:27]
	v_mfma_f32_16x16x32_bf16 v[12:15], v[76:79], v[208:211], v[12:15]
	v_mfma_f32_16x16x32_bf16 v[8:11], v[88:91], v[208:211], v[8:11]
	v_mfma_f32_16x16x32_bf16 v[60:63], v[84:87], v[180:183], v[60:63]
	v_mfma_f32_16x16x32_bf16 v[56:59], v[96:99], v[180:183], v[56:59]
	v_mfma_f32_16x16x32_bf16 v[44:47], v[84:87], v[196:199], v[44:47]
	v_mfma_f32_16x16x32_bf16 v[40:43], v[96:99], v[196:199], v[40:43]
	v_mfma_f32_16x16x32_bf16 v[28:31], v[84:87], v[204:207], v[28:31]
	v_mfma_f32_16x16x32_bf16 v[24:27], v[96:99], v[204:207], v[24:27]
	v_mfma_f32_16x16x32_bf16 v[12:15], v[84:87], v[212:215], v[12:15]
	v_mfma_f32_16x16x32_bf16 v[8:11], v[96:99], v[212:215], v[8:11]
	v_mfma_f32_16x16x32_bf16 v[52:55], v[144:147], v[176:179], v[52:55]
	v_mfma_f32_16x16x32_bf16 v[48:51], v[152:155], v[176:179], v[48:51]
	v_mfma_f32_16x16x32_bf16 v[36:39], v[144:147], v[184:187], v[36:39]
	v_mfma_f32_16x16x32_bf16 v[32:35], v[152:155], v[184:187], v[32:35]
	v_mfma_f32_16x16x32_bf16 v[20:23], v[144:147], v[200:203], v[20:23]
	v_mfma_f32_16x16x32_bf16 v[16:19], v[152:155], v[200:203], v[16:19]
	v_mfma_f32_16x16x32_bf16 v[4:7], v[144:147], v[208:211], v[4:7]
	v_mfma_f32_16x16x32_bf16 v[0:3], v[152:155], v[208:211], v[0:3]
	v_mfma_f32_16x16x32_bf16 v[52:55], v[148:151], v[180:183], v[52:55]
	v_mfma_f32_16x16x32_bf16 v[48:51], v[156:159], v[180:183], v[48:51]
	v_mfma_f32_16x16x32_bf16 v[36:39], v[148:151], v[196:199], v[36:39]
	v_mfma_f32_16x16x32_bf16 v[32:35], v[156:159], v[196:199], v[32:35]
	v_mfma_f32_16x16x32_bf16 v[20:23], v[148:151], v[204:207], v[20:23]
	v_mfma_f32_16x16x32_bf16 v[16:19], v[156:159], v[204:207], v[16:19]
	v_mfma_f32_16x16x32_bf16 v[4:7], v[148:151], v[212:215], v[4:7]
	v_mfma_f32_16x16x32_bf16 v[0:3], v[156:159], v[212:215], v[0:3]
	s_barrier
	s_setprio 0
	s_add_i32 s69, s69, 2
	s_add_u32 s40, s40, 0x100
	s_addc_u32 s41, s41, 0
	s_add_u32 s67, s67, 0x100
	s_addc_u32 s68, s68, 0
	s_cmp_gt_u32 s69, 61
	s_cbranch_scc0 .LBB8_961
	s_and_b64 vcc, exec, s[14:15]
	s_cbranch_vccz .LBB8_964
	s_barrier

.LBB8_1038:
	v_readlane_b32 s8, v254, 47
	v_readlane_b32 s9, v254, 48
	s_mov_b64 s[4:5], s[8:9]
	s_cmp_lt_i32 s4, 9
	s_cselect_b64 s[0:1], -1, 0
	s_cmp_gt_i32 s5, 8
	s_cselect_b64 s[4:5], -1, 0
	s_and_b64 s[4:5], s[0:1], s[4:5]
	s_andn2_b64 vcc, exec, s[4:5]
	v_readlane_b32 s10, v254, 49
	v_readlane_b32 s11, v254, 50
	s_cbranch_vccnz .LBB8_1061
	s_waitcnt vmcnt(0) lgkmcnt(0)
	v_mbcnt_lo_u32_b32 v9, -1, 0
	v_mbcnt_hi_u32_b32 v9, -1, v9
	s_cmpk_gt_i32 s2, 0x7ff
	v_add_u32_e32 v0, s96, v9
	s_nop 0
	v_readfirstlane_b32 s1, v0
	s_cbranch_scc1 .LBB8_1061
	v_lshlrev_b32_e32 v1, 4, v0
	v_add_u32_e32 v2, 0x2000, v1
	v_ashrrev_i32_e32 v3, 31, v2
	v_lshrrev_b32_e32 v3, 22, v3
	v_add_u32_e32 v3, v2, v3
	v_ashrrev_i32_e32 v8, 10, v3
	v_mul_i32_i24_e32 v3, 0x400, v8
	v_sub_u32_e32 v2, v2, v3
	v_lshrrev_b32_e32 v3, 4, v2
	v_bitop3_b32 v2, v3, v2, 32 bitop3:0x6c
	v_ashrrev_i32_e32 v3, 31, v2
	v_lshrrev_b32_e32 v3, 26, v3
	v_add_u32_e32 v3, v2, v3
	v_lshlrev_b32_e32 v4, 3, v8
	v_ashrrev_i32_e32 v10, 6, v3
	v_and_b32_e32 v4, -16, v4
	v_add_u32_e32 v4, v10, v4
	v_and_b32_e32 v5, 3, v10
	s_mov_b32 s0, 0x7ffe0
	v_lshrrev_b32_e32 v6, 2, v4
	v_lshlrev_b32_e32 v7, 1, v4
	v_and_b32_e32 v3, 0xc0, v3
	v_and_or_b32 v5, v4, s0, v5
	v_and_b32_e32 v6, 4, v6
	v_and_b32_e32 v7, 24, v7
	v_sub_u32_e32 v2, v2, v3
	v_mov_b32_e32 v3, 1
	v_or3_b32 v5, v5, v6, v7
	v_lshlrev_b32_e32 v6, 5, v8
	v_ashrrev_i16_sdwa v2, v3, sext(v2) dst_sel:DWORD dst_unused:UNUSED_PAD src0_sel:DWORD src1_sel:BYTE_0
	v_and_b32_e32 v6, 32, v6
	v_bfe_i32 v11, v2, 0, 16
	v_add_lshl_u32 v2, v6, v11, 1
	v_lshl_add_u32 v144, v5, 13, v2
	v_lshl_add_u32 v146, v4, 13, v2
	v_bfe_i32 v2, v0, 27, 1
	v_lshrrev_b32_e32 v2, 22, v2
	v_add_u32_e32 v2, v1, v2
	v_and_b32_e32 v2, 0xfffffc00, v2
	v_sub_u32_e32 v1, v1, v2
	v_lshrrev_b32_e32 v2, 4, v1
	v_ashrrev_i32_e32 v4, 31, v0
	v_bitop3_b32 v1, v2, v1, 32 bitop3:0x6c
	v_lshrrev_b32_e32 v4, 26, v4
	v_ashrrev_i32_e32 v2, 31, v1
	v_add_u32_e32 v0, v0, v4
	v_lshrrev_b32_e32 v2, 26, v2
	v_ashrrev_i32_e32 v13, 6, v0
	v_add_u32_e32 v2, v1, v2
	v_lshlrev_b32_e32 v0, 3, v13
	v_ashrrev_i32_e32 v12, 6, v2
	v_and_b32_e32 v0, -16, v0
	v_add_u32_e32 v0, v12, v0
	v_and_b32_e32 v4, 3, v12
	s_ashr_i32 s38, s2, 31
	v_and_or_b32 v4, v0, s0, v4
	s_lshr_b32 s0, s38, 29
	s_add_i32 s0, s2, s0
	s_and_b32 s8, s0, -8
	s_ashr_i32 s10, s1, 6
	s_sub_i32 s8, s2, s8
	s_ashr_i32 s12, s1, 8
	s_lshl_b32 s33, s10, 10
	s_lshl_b32 s11, s8, 8
	s_ashr_i32 s0, s0, 3
	s_mul_i32 s9, s8, 0x101
	s_cmp_lt_i32 s8, 0
	s_cselect_b32 s8, s9, s11
	s_add_i32 s0, s8, s0
	s_ashr_i32 s8, s0, 31
	s_lshr_b32 s8, s8, 23
	s_add_i32 s8, s0, s8
	s_ashr_i32 s9, s8, 9
	s_and_b32 s8, s8, 0xfffffe00
	s_sub_i32 s8, s0, s8
	s_sext_i32_i16 s0, s8
	s_bfe_u32 s0, s0, 0x3001c
	s_add_i32 s11, s8, s0
	s_sext_i32_i16 s0, s11
	s_and_b32 s11, s11, 0xfff8
	s_sub_i32 s8, s8, s11
	s_lshl_b32 s9, s9, 3
	s_sext_i32_i16 s8, s8
	v_lshrrev_b32_e32 v5, 2, v0
	v_lshlrev_b32_e32 v6, 1, v0
	v_and_b32_e32 v2, 0xc0, v2
	s_lshr_b32 s0, s0, 3
	s_add_i32 s42, s9, s8
	v_and_b32_e32 v5, 4, v5
	v_and_b32_e32 v6, 24, v6
	v_sub_u32_e32 v1, v1, v2
	s_ashr_i32 s43, s42, 31
	s_bfe_i64 s[14:15], s[0:1], 0x100000
	v_or3_b32 v4, v4, v5, v6
	v_lshlrev_b32_e32 v5, 5, v13
	v_ashrrev_i16_sdwa v1, v3, sext(v1) dst_sel:DWORD dst_unused:UNUSED_PAD src0_sel:DWORD src1_sel:BYTE_0
	s_lshl_b64 s[8:9], s[42:43], 21
	s_lshl_b64 s[14:15], s[14:15], 21
	v_and_b32_e32 v5, 32, v5
	v_bfe_i32 v14, v1, 0, 16
	s_add_u32 s28, s92, s14
	v_add_lshl_u32 v1, v5, v14, 1
	s_addc_u32 s29, s93, s15
	s_add_i32 s39, s33, 0
	v_lshl_add_u32 v148, v4, 13, v1
	s_add_i32 m0, s39, 0x10000
	v_lshl_add_u32 v150, v0, 13, v1
	global_load_lds_dwordx4 v148, s[28:29]
	s_add_i32 m0, s39, 0x12000
	s_add_u32 s14, s28, 0x100000
	global_load_lds_dwordx4 v144, s[28:29]
	s_addc_u32 s15, s29, 0
	s_add_i32 m0, s39, 0x14000
	v_mov_b32_e32 v149, 0
	global_load_lds_dwordx4 v148, s[14:15]
	s_add_i32 m0, s39, 0x16000
	s_add_u32 s44, s54, s8
	s_addc_u32 s45, s55, s9
	s_add_i32 s46, s39, 0x2000
	global_load_lds_dwordx4 v144, s[14:15]
	s_mov_b32 m0, s39
	s_add_u32 s8, s44, 0x100000
	global_load_lds_dwordx4 v150, s[44:45]
	s_mov_b32 m0, s46
	s_addc_u32 s9, s45, 0
	s_add_i32 s47, s39, 0x4000
	global_load_lds_dwordx4 v146, s[44:45]
	s_mov_b32 m0, s47
	s_add_i32 s48, s39, 0x6000
	global_load_lds_dwordx4 v150, s[8:9]
	s_mov_b32 m0, s48
	v_mov_b32_e32 v145, v149
	global_load_lds_dwordx4 v146, s[8:9]
	v_mov_b32_e32 v151, v149
	v_mov_b32_e32 v147, v149
	s_cmp_eq_u32 s12, 1
	v_lshl_add_u64 v[6:7], s[28:29], 0, v[148:149]
	v_lshl_add_u64 v[4:5], s[28:29], 0, v[144:145]
	v_lshl_add_u64 v[0:1], s[44:45], 0, v[150:151]
	s_cselect_b64 s[8:9], -1, 0
	s_cmp_lg_u32 s12, 1
	v_lshl_add_u64 v[2:3], s[44:45], 0, v[146:147]
	s_cbranch_scc1 .LBB8_1042
	s_barrier
.LBB8_1042:
	s_lshl_b32 s10, s10, 5
	s_and_b32 s16, s10, 0x60
	s_mov_b64 s[10:11], 0x80
	s_add_i32 m0, s39, 0x18000
	v_lshl_add_u64 v[6:7], v[6:7], 0, s[10:11]
	s_ashr_i32 s49, s3, 31
	s_lshl_b32 s13, s12, 13
	s_lshl_b32 s17, s16, 7
	s_waitcnt vmcnt(2)
	s_barrier
	global_load_lds_dwordx4 v[6:7], off
	v_lshl_add_u64 v[4:5], v[4:5], 0, s[10:11]
	s_add_i32 m0, s39, 0x1a000
	s_add_i32 s52, s39, 0x8000
	s_add_i32 s53, s39, 0xa000
	global_load_lds_dwordx4 v[4:5], off
	v_lshl_add_u64 v[0:1], v[0:1], 0, s[10:11]
	s_mov_b32 m0, s52
	s_add_u32 s14, s28, 0x100080
	global_load_lds_dwordx4 v[0:1], off
	v_lshl_add_u64 v[0:1], v[2:3], 0, s[10:11]
	s_mov_b32 m0, s53
	s_addc_u32 s15, s29, 0
	global_load_lds_dwordx4 v[0:1], off
	s_add_i32 m0, s39, 0x1c000
	v_lshl_add_u64 v[0:1], s[14:15], 0, v[148:149]
	global_load_lds_dwordx4 v[0:1], off
	v_lshl_add_u64 v[0:1], s[14:15], 0, v[144:145]
	s_add_i32 m0, s39, 0x1e000
	v_mov_b32_e32 v3, v149
	global_load_lds_dwordx4 v[0:1], off
	v_lshrrev_b32_e32 v1, 1, v9
	v_and_b32_e32 v1, 24, v1
	v_and_b32_e32 v0, 15, v9
	v_lshlrev_b32_e32 v2, 1, v1
	v_lshl_or_b32 v166, s12, 6, v0
	v_lshl_or_b32 v0, v0, 6, v2
	v_lshlrev_b32_e32 v2, 2, v9
	v_and_b32_e32 v2, 32, v2
	v_bitop3_b32 v4, v0, s13, v2 bitop3:0xde
	v_bitop3_b32 v167, s17, v0, v2 bitop3:0xf6
	v_lshlrev_b32_e32 v0, 16, v13
	v_and_b32_e32 v0, 0xfffe0000, v0
	v_or_b32_e32 v168, s16, v1
	v_lshl_add_u32 v0, v12, 13, v0
	v_and_b32_e32 v1, 1, v13
	v_lshl_or_b32 v0, v1, 6, v0
	v_lshl_add_u32 v152, v14, 1, v0
	v_lshlrev_b32_e32 v0, 16, v8
	v_and_b32_e32 v0, 0xfffe0000, v0
	v_lshl_add_u32 v0, v10, 13, v0
	v_and_b32_e32 v1, 1, v8
	s_waitcnt vmcnt(6)
	v_lshl_or_b32 v0, v1, 6, v0
	v_mov_b32_e32 v2, v149
	s_cmpk_lt_u32 s1, 0x100
	v_lshl_add_u32 v154, v11, 1, v0
	v_mov_b32_e32 v0, v149
	v_mov_b32_e32 v1, v149
	v_add_u32_e32 v169, 0, v4
	v_mov_b64_e32 v[14:15], v[2:3]
	v_mov_b64_e32 v[10:11], v[2:3]
	v_mov_b64_e32 v[6:7], v[2:3]
	s_sext_i32_i16 s43, s0
	s_cselect_b64 s[12:13], -1, 0
	v_mov_b32_e32 v153, v149
	v_mov_b32_e32 v155, v149
	s_mov_b32 s56, 0
	v_mov_b64_e32 v[156:157], 0x7ff
	s_add_i32 s57, 0, 0x10000
	s_add_i32 s58, 0, 0x14000
	v_mov_b32_e32 v170, 0x358637bd
	s_mov_b64 s[14:15], 0x400000
	s_mov_b32 s59, 0x400000
	s_mov_b64 s[16:17], 0x480000
	s_mov_b32 s60, 0x480000
	s_mov_b64 s[18:19], 0x500000
	s_mov_b32 s61, 0x500000
	s_mov_b64 s[20:21], 0x580000
	s_mov_b32 s62, 0x580000
	v_mov_b32_e32 v172, v149
	v_mov_b32_e32 v177, v149
	v_mov_b32_e32 v173, v149
	v_mov_b64_e32 v[12:13], v[0:1]
	v_mov_b64_e32 v[8:9], v[0:1]
	v_mov_b64_e32 v[4:5], v[0:1]
	v_mov_b32_e32 v178, v149
	v_mov_b32_e32 v176, v149
	v_mov_b32_e32 v175, v149
	v_mov_b32_e32 v174, v149
	v_mov_b32_e32 v171, v149
	s_barrier
	s_branch .LBB8_1045

.LBB8_1052:
	v_add_u32_e32 v179, s57, v167
	ds_read_b128 v[180:183], v179
	ds_read_b128 v[184:187], v179 offset:1024
	ds_read_b128 v[188:191], v179 offset:2048
	ds_read_b128 v[192:195], v179 offset:3072
	v_add_u32_e32 v179, s58, v167
	ds_read_b128 v[196:199], v179
	ds_read_b128 v[200:203], v179 offset:1024
	ds_read_b128 v[204:207], v179 offset:2048
	ds_read_b128 v[208:211], v179 offset:3072
	s_add_u32 s44, s42, 0xfff00080
	s_addc_u32 s45, s43, -1
	s_and_b64 s[28:29], s[28:29], exec
	s_cselect_b32 s45, s25, s45
	s_cselect_b32 s44, s63, s44
	s_cselect_b32 s29, s23, s66
	s_cselect_b32 s28, s64, s65
	v_lshl_add_u64 v[244:245], s[42:43], 0, v[152:153]
	s_add_i32 m0, s39, 0xc000
	ds_read_b128 v[212:215], v169
	ds_read_b128 v[216:219], v169 offset:1024
	ds_read_b128 v[220:223], v169 offset:2048
	ds_read_b128 v[224:227], v169 offset:3072
	ds_read_b128 v[228:231], v169 offset:4096
	ds_read_b128 v[232:235], v169 offset:5120
	ds_read_b128 v[236:239], v169 offset:6144
	ds_read_b128 v[240:243], v169 offset:7168
	global_load_lds_dwordx4 v[244:245], off
	v_lshl_add_u64 v[244:245], s[42:43], 0, v[154:155]
	s_add_i32 m0, s39, 0xe000
	s_nop 0
	global_load_lds_dwordx4 v[244:245], off
	s_waitcnt vmcnt(8)
	s_waitcnt lgkmcnt(0)
	s_setprio 1
	s_barrier
	v_mfma_f32_16x16x32_bf16 v[140:143], v[180:183], v[212:215], v[140:143]
	v_mfma_f32_16x16x32_bf16 v[136:139], v[188:191], v[212:215], v[136:139]
	v_mfma_f32_16x16x32_bf16 v[124:127], v[180:183], v[220:223], v[124:127]
	v_mfma_f32_16x16x32_bf16 v[120:123], v[188:191], v[220:223], v[120:123]
	v_mfma_f32_16x16x32_bf16 v[108:111], v[180:183], v[228:231], v[108:111]
	v_mfma_f32_16x16x32_bf16 v[104:107], v[188:191], v[228:231], v[104:107]
	v_mfma_f32_16x16x32_bf16 v[92:95], v[180:183], v[236:239], v[92:95]
	v_mfma_f32_16x16x32_bf16 v[88:91], v[188:191], v[236:239], v[88:91]
	v_mfma_f32_16x16x32_bf16 v[140:143], v[184:187], v[216:219], v[140:143]
	v_mfma_f32_16x16x32_bf16 v[136:139], v[192:195], v[216:219], v[136:139]
	v_mfma_f32_16x16x32_bf16 v[124:127], v[184:187], v[224:227], v[124:127]
	v_mfma_f32_16x16x32_bf16 v[120:123], v[192:195], v[224:227], v[120:123]
	v_mfma_f32_16x16x32_bf16 v[108:111], v[184:187], v[232:235], v[108:111]
	v_mfma_f32_16x16x32_bf16 v[104:107], v[192:195], v[232:235], v[104:107]
	v_mfma_f32_16x16x32_bf16 v[92:95], v[184:187], v[240:243], v[92:95]
	v_mfma_f32_16x16x32_bf16 v[88:91], v[192:195], v[240:243], v[88:91]
	v_mfma_f32_16x16x32_bf16 v[132:135], v[196:199], v[212:215], v[132:135]
	v_mfma_f32_16x16x32_bf16 v[128:131], v[204:207], v[212:215], v[128:131]
	v_mfma_f32_16x16x32_bf16 v[116:119], v[196:199], v[220:223], v[116:119]
	v_mfma_f32_16x16x32_bf16 v[112:115], v[204:207], v[220:223], v[112:115]
	v_mfma_f32_16x16x32_bf16 v[100:103], v[196:199], v[228:231], v[100:103]
	v_mfma_f32_16x16x32_bf16 v[96:99], v[204:207], v[228:231], v[96:99]
	v_mfma_f32_16x16x32_bf16 v[84:87], v[196:199], v[236:239], v[84:87]
	v_mfma_f32_16x16x32_bf16 v[80:83], v[204:207], v[236:239], v[80:83]
	v_mfma_f32_16x16x32_bf16 v[132:135], v[200:203], v[216:219], v[132:135]
	v_mfma_f32_16x16x32_bf16 v[128:131], v[208:211], v[216:219], v[128:131]
	v_mfma_f32_16x16x32_bf16 v[116:119], v[200:203], v[224:227], v[116:119]
	v_mfma_f32_16x16x32_bf16 v[112:115], v[208:211], v[224:227], v[112:115]
	v_mfma_f32_16x16x32_bf16 v[100:103], v[200:203], v[232:235], v[100:103]
	v_mfma_f32_16x16x32_bf16 v[96:99], v[208:211], v[232:235], v[96:99]
	v_mfma_f32_16x16x32_bf16 v[84:87], v[200:203], v[240:243], v[84:87]
	v_mfma_f32_16x16x32_bf16 v[80:83], v[208:211], v[240:243], v[80:83]
	s_barrier
	s_setprio 0
	s_add_i32 s68, s57, s33
	v_lshl_add_u64 v[244:245], s[28:29], 0, v[148:149]
	s_mov_b32 m0, s68
	ds_read_b128 v[212:215], v169 offset:16384
	ds_read_b128 v[216:219], v169 offset:17408
	ds_read_b128 v[220:223], v169 offset:18432
	ds_read_b128 v[224:227], v169 offset:19456
	ds_read_b128 v[228:231], v169 offset:20480
	ds_read_b128 v[232:235], v169 offset:21504
	ds_read_b128 v[236:239], v169 offset:22528
	ds_read_b128 v[240:243], v169 offset:23552
	global_load_lds_dwordx4 v[244:245], off
	s_add_i32 m0, s68, 0x2000
	s_add_u32 s68, s28, 0x100000
	v_lshl_add_u64 v[246:247], s[28:29], 0, v[144:145]
	s_addc_u32 s69, s29, 0
	s_add_i32 s70, s58, s33
	global_load_lds_dwordx4 v[246:247], off
	v_lshl_add_u64 v[248:249], s[68:69], 0, v[148:149]
	s_mov_b32 m0, s70
	v_lshl_add_u64 v[250:251], s[44:45], 0, v[146:147]
	global_load_lds_dwordx4 v[248:249], off
	v_lshl_add_u64 v[248:249], s[68:69], 0, v[144:145]
	s_add_i32 m0, s70, 0x2000
	s_nop 0
	global_load_lds_dwordx4 v[248:249], off
	v_lshl_add_u64 v[248:249], s[44:45], 0, v[150:151]
	s_mov_b32 m0, s39
	s_nop 0
	global_load_lds_dwordx4 v[248:249], off
	s_mov_b32 m0, s46
	s_nop 0
	global_load_lds_dwordx4 v[250:251], off
	s_waitcnt vmcnt(8)
	s_waitcnt lgkmcnt(0)
	s_setprio 1
	s_barrier
	v_mfma_f32_16x16x32_bf16 v[76:79], v[180:183], v[212:215], v[76:79]
	v_mfma_f32_16x16x32_bf16 v[72:75], v[188:191], v[212:215], v[72:75]
	v_mfma_f32_16x16x32_bf16 v[60:63], v[180:183], v[220:223], v[60:63]
	v_mfma_f32_16x16x32_bf16 v[56:59], v[188:191], v[220:223], v[56:59]
	v_mfma_f32_16x16x32_bf16 v[44:47], v[180:183], v[228:231], v[44:47]
	v_mfma_f32_16x16x32_bf16 v[40:43], v[188:191], v[228:231], v[40:43]
	v_mfma_f32_16x16x32_bf16 v[28:31], v[180:183], v[236:239], v[28:31]
	v_mfma_f32_16x16x32_bf16 v[24:27], v[188:191], v[236:239], v[24:27]
	v_mfma_f32_16x16x32_bf16 v[76:79], v[184:187], v[216:219], v[76:79]
	v_mfma_f32_16x16x32_bf16 v[72:75], v[192:195], v[216:219], v[72:75]
	v_mfma_f32_16x16x32_bf16 v[60:63], v[184:187], v[224:227], v[60:63]
	v_mfma_f32_16x16x32_bf16 v[56:59], v[192:195], v[224:227], v[56:59]
	v_mfma_f32_16x16x32_bf16 v[44:47], v[184:187], v[232:235], v[44:47]
	v_mfma_f32_16x16x32_bf16 v[40:43], v[192:195], v[232:235], v[40:43]
	v_mfma_f32_16x16x32_bf16 v[28:31], v[184:187], v[240:243], v[28:31]
	v_mfma_f32_16x16x32_bf16 v[24:27], v[192:195], v[240:243], v[24:27]
	v_mfma_f32_16x16x32_bf16 v[68:71], v[196:199], v[212:215], v[68:71]
	v_mfma_f32_16x16x32_bf16 v[64:67], v[204:207], v[212:215], v[64:67]
	v_mfma_f32_16x16x32_bf16 v[52:55], v[196:199], v[220:223], v[52:55]
	v_mfma_f32_16x16x32_bf16 v[48:51], v[204:207], v[220:223], v[48:51]
	v_mfma_f32_16x16x32_bf16 v[36:39], v[196:199], v[228:231], v[36:39]
	v_mfma_f32_16x16x32_bf16 v[32:35], v[204:207], v[228:231], v[32:35]
	v_mfma_f32_16x16x32_bf16 v[20:23], v[196:199], v[236:239], v[20:23]
	v_mfma_f32_16x16x32_bf16 v[16:19], v[204:207], v[236:239], v[16:19]
	v_mfma_f32_16x16x32_bf16 v[68:71], v[200:203], v[216:219], v[68:71]
	v_mfma_f32_16x16x32_bf16 v[64:67], v[208:211], v[216:219], v[64:67]
	v_mfma_f32_16x16x32_bf16 v[52:55], v[200:203], v[224:227], v[52:55]
	v_mfma_f32_16x16x32_bf16 v[48:51], v[208:211], v[224:227], v[48:51]
	v_mfma_f32_16x16x32_bf16 v[36:39], v[200:203], v[232:235], v[36:39]
	v_mfma_f32_16x16x32_bf16 v[32:35], v[208:211], v[232:235], v[32:35]
	v_mfma_f32_16x16x32_bf16 v[20:23], v[200:203], v[240:243], v[20:23]
	v_mfma_f32_16x16x32_bf16 v[16:19], v[208:211], v[240:243], v[16:19]
	s_barrier
	s_setprio 0
	s_add_i32 s68, 0, 0x18000
	v_add_u32_e32 v179, s68, v167
	s_add_i32 s69, 0, 0x1c000
	ds_read_b128 v[180:183], v179
	ds_read_b128 v[184:187], v179 offset:1024
	ds_read_b128 v[188:191], v179 offset:2048
	ds_read_b128 v[192:195], v179 offset:3072
	v_add_u32_e32 v179, s69, v167
	ds_read_b128 v[196:199], v179
	ds_read_b128 v[200:203], v179 offset:1024
	ds_read_b128 v[204:207], v179 offset:2048
	ds_read_b128 v[208:211], v179 offset:3072
	s_add_u32 s44, s44, 0x100000
	s_addc_u32 s45, s45, 0
	s_mov_b32 m0, s47
	v_lshl_add_u64 v[252:253], s[44:45], 0, v[150:151]
	ds_read_b128 v[212:215], v169 offset:32768
	ds_read_b128 v[216:219], v169 offset:33792
	ds_read_b128 v[220:223], v169 offset:34816
	ds_read_b128 v[224:227], v169 offset:35840
	ds_read_b128 v[228:231], v169 offset:36864
	ds_read_b128 v[232:235], v169 offset:37888
	ds_read_b128 v[236:239], v169 offset:38912
	ds_read_b128 v[240:243], v169 offset:39936
	global_load_lds_dwordx4 v[252:253], off
	v_lshl_add_u64 v[252:253], s[44:45], 0, v[146:147]
	s_mov_b32 m0, s48
	s_nop 0
	global_load_lds_dwordx4 v[252:253], off
	s_waitcnt vmcnt(8)
	s_waitcnt lgkmcnt(0)
	s_setprio 1
	s_barrier
	v_mfma_f32_16x16x32_bf16 v[140:143], v[180:183], v[212:215], v[140:143]
	v_mfma_f32_16x16x32_bf16 v[136:139], v[188:191], v[212:215], v[136:139]
	v_mfma_f32_16x16x32_bf16 v[124:127], v[180:183], v[220:223], v[124:127]
	v_mfma_f32_16x16x32_bf16 v[120:123], v[188:191], v[220:223], v[120:123]
	v_mfma_f32_16x16x32_bf16 v[108:111], v[180:183], v[228:231], v[108:111]
	v_mfma_f32_16x16x32_bf16 v[104:107], v[188:191], v[228:231], v[104:107]
	v_mfma_f32_16x16x32_bf16 v[92:95], v[180:183], v[236:239], v[92:95]
	v_mfma_f32_16x16x32_bf16 v[88:91], v[188:191], v[236:239], v[88:91]
	v_mfma_f32_16x16x32_bf16 v[140:143], v[184:187], v[216:219], v[140:143]
	v_mfma_f32_16x16x32_bf16 v[136:139], v[192:195], v[216:219], v[136:139]
	v_mfma_f32_16x16x32_bf16 v[124:127], v[184:187], v[224:227], v[124:127]
	v_mfma_f32_16x16x32_bf16 v[120:123], v[192:195], v[224:227], v[120:123]
	v_mfma_f32_16x16x32_bf16 v[108:111], v[184:187], v[232:235], v[108:111]
	v_mfma_f32_16x16x32_bf16 v[104:107], v[192:195], v[232:235], v[104:107]
	v_mfma_f32_16x16x32_bf16 v[92:95], v[184:187], v[240:243], v[92:95]
	v_mfma_f32_16x16x32_bf16 v[88:91], v[192:195], v[240:243], v[88:91]
	v_mfma_f32_16x16x32_bf16 v[132:135], v[196:199], v[212:215], v[132:135]
	v_mfma_f32_16x16x32_bf16 v[128:131], v[204:207], v[212:215], v[128:131]
	v_mfma_f32_16x16x32_bf16 v[116:119], v[196:199], v[220:223], v[116:119]
	v_mfma_f32_16x16x32_bf16 v[112:115], v[204:207], v[220:223], v[112:115]
	v_mfma_f32_16x16x32_bf16 v[100:103], v[196:199], v[228:231], v[100:103]
	v_mfma_f32_16x16x32_bf16 v[96:99], v[204:207], v[228:231], v[96:99]
	v_mfma_f32_16x16x32_bf16 v[84:87], v[196:199], v[236:239], v[84:87]
	v_mfma_f32_16x16x32_bf16 v[80:83], v[204:207], v[236:239], v[80:83]
	v_mfma_f32_16x16x32_bf16 v[132:135], v[200:203], v[216:219], v[132:135]
	v_mfma_f32_16x16x32_bf16 v[128:131], v[208:211], v[216:219], v[128:131]
	v_mfma_f32_16x16x32_bf16 v[116:119], v[200:203], v[224:227], v[116:119]
	v_mfma_f32_16x16x32_bf16 v[112:115], v[208:211], v[224:227], v[112:115]
	v_mfma_f32_16x16x32_bf16 v[100:103], v[200:203], v[232:235], v[100:103]
	v_mfma_f32_16x16x32_bf16 v[96:99], v[208:211], v[232:235], v[96:99]
	v_mfma_f32_16x16x32_bf16 v[84:87], v[200:203], v[240:243], v[84:87]
	v_mfma_f32_16x16x32_bf16 v[80:83], v[208:211], v[240:243], v[80:83]
	s_barrier
	s_setprio 0
	s_add_i32 s44, s68, s33
	v_lshl_add_u64 v[244:245], v[244:245], 0, s[10:11]
	s_mov_b32 m0, s44
	ds_read_b128 v[212:215], v169 offset:49152
	ds_read_b128 v[216:219], v169 offset:50176
	ds_read_b128 v[220:223], v169 offset:51200
	ds_read_b128 v[224:227], v169 offset:52224
	ds_read_b128 v[228:231], v169 offset:53248
	ds_read_b128 v[232:235], v169 offset:54272
	ds_read_b128 v[236:239], v169 offset:55296
	ds_read_b128 v[240:243], v169 offset:56320
	global_load_lds_dwordx4 v[244:245], off
	s_add_i32 m0, s44, 0x2000
	s_add_u32 s28, s28, 0x100080
	v_lshl_add_u64 v[244:245], v[246:247], 0, s[10:11]
	s_addc_u32 s29, s29, 0
	s_add_i32 s44, s69, s33
	global_load_lds_dwordx4 v[244:245], off
	v_lshl_add_u64 v[244:245], s[28:29], 0, v[148:149]
	s_mov_b32 m0, s44
	s_nop 0
	global_load_lds_dwordx4 v[244:245], off
	v_lshl_add_u64 v[244:245], s[28:29], 0, v[144:145]
	s_add_i32 m0, s44, 0x2000
	s_nop 0
	global_load_lds_dwordx4 v[244:245], off
	v_lshl_add_u64 v[244:245], v[248:249], 0, s[10:11]
	s_mov_b32 m0, s52
	s_nop 0
	global_load_lds_dwordx4 v[244:245], off
	v_lshl_add_u64 v[244:245], v[250:251], 0, s[10:11]
	s_mov_b32 m0, s53
	s_nop 0
	global_load_lds_dwordx4 v[244:245], off
	s_waitcnt vmcnt(8)
	s_waitcnt lgkmcnt(0)
	s_setprio 1
	s_barrier
	v_mfma_f32_16x16x32_bf16 v[76:79], v[180:183], v[212:215], v[76:79]
	v_mfma_f32_16x16x32_bf16 v[72:75], v[188:191], v[212:215], v[72:75]
	v_mfma_f32_16x16x32_bf16 v[60:63], v[180:183], v[220:223], v[60:63]
	v_mfma_f32_16x16x32_bf16 v[56:59], v[188:191], v[220:223], v[56:59]
	v_mfma_f32_16x16x32_bf16 v[44:47], v[180:183], v[228:231], v[44:47]
	v_mfma_f32_16x16x32_bf16 v[40:43], v[188:191], v[228:231], v[40:43]
	v_mfma_f32_16x16x32_bf16 v[28:31], v[180:183], v[236:239], v[28:31]
	v_mfma_f32_16x16x32_bf16 v[24:27], v[188:191], v[236:239], v[24:27]
	v_mfma_f32_16x16x32_bf16 v[76:79], v[184:187], v[216:219], v[76:79]
	v_mfma_f32_16x16x32_bf16 v[72:75], v[192:195], v[216:219], v[72:75]
	v_mfma_f32_16x16x32_bf16 v[60:63], v[184:187], v[224:227], v[60:63]
	v_mfma_f32_16x16x32_bf16 v[56:59], v[192:195], v[224:227], v[56:59]
	v_mfma_f32_16x16x32_bf16 v[44:47], v[184:187], v[232:235], v[44:47]
	v_mfma_f32_16x16x32_bf16 v[40:43], v[192:195], v[232:235], v[40:43]
	v_mfma_f32_16x16x32_bf16 v[28:31], v[184:187], v[240:243], v[28:31]
	v_mfma_f32_16x16x32_bf16 v[24:27], v[192:195], v[240:243], v[24:27]
	v_mfma_f32_16x16x32_bf16 v[68:71], v[196:199], v[212:215], v[68:71]
	v_mfma_f32_16x16x32_bf16 v[64:67], v[204:207], v[212:215], v[64:67]
	v_mfma_f32_16x16x32_bf16 v[52:55], v[196:199], v[220:223], v[52:55]
	v_mfma_f32_16x16x32_bf16 v[48:51], v[204:207], v[220:223], v[48:51]
	v_mfma_f32_16x16x32_bf16 v[36:39], v[196:199], v[228:231], v[36:39]
	v_mfma_f32_16x16x32_bf16 v[32:35], v[204:207], v[228:231], v[32:35]
	v_mfma_f32_16x16x32_bf16 v[20:23], v[196:199], v[236:239], v[20:23]
	v_mfma_f32_16x16x32_bf16 v[16:19], v[204:207], v[236:239], v[16:19]
	v_mfma_f32_16x16x32_bf16 v[68:71], v[200:203], v[216:219], v[68:71]
	v_mfma_f32_16x16x32_bf16 v[64:67], v[208:211], v[216:219], v[64:67]
	v_mfma_f32_16x16x32_bf16 v[52:55], v[200:203], v[224:227], v[52:55]
	v_mfma_f32_16x16x32_bf16 v[48:51], v[208:211], v[224:227], v[48:51]
	v_mfma_f32_16x16x32_bf16 v[36:39], v[200:203], v[232:235], v[36:39]
	v_mfma_f32_16x16x32_bf16 v[32:35], v[208:211], v[232:235], v[32:35]
	v_mfma_f32_16x16x32_bf16 v[20:23], v[200:203], v[240:243], v[20:23]
	v_mfma_f32_16x16x32_bf16 v[16:19], v[208:211], v[240:243], v[16:19]
	s_barrier
	s_setprio 0
	s_add_i32 s67, s67, 2
	s_add_u32 s42, s42, 0x100
	s_addc_u32 s43, s43, 0
	s_add_u32 s65, s65, 0x100
	s_addc_u32 s66, s66, 0
	s_cmp_gt_u32 s67, 61
	s_cbranch_scc1 .LBB8_1055
.LBB8_1053:
	s_cmp_eq_u32 s67, 60
	s_cselect_b64 s[28:29], -1, 0
	s_cmp_lg_u32 s67, 60
	s_cbranch_scc1 .LBB8_1052
	global_load_dword v171, v[164:165], off offset:0
	global_load_dword v174, v[164:165], off offset:64
	global_load_dword v175, v[164:165], off offset:128
	global_load_dword v176, v[164:165], off offset:192
	global_load_dword v178, v[164:165], off offset:512
	global_load_dword v173, v[164:165], off offset:576
	global_load_dword v172, v[164:165], off offset:640
	global_load_dword v177, v[164:165], off offset:704
	global_load_dwordx4 v[4:7], v[162:163], off offset:0
	global_load_dwordx4 v[8:11], v[162:163], off offset:16
	global_load_dwordx4 v[12:15], v[162:163], off offset:512
	global_load_dwordx4 v[0:3], v[162:163], off offset:528
	s_branch .LBB8_1052

.LBB8_1057:
	v_lshlrev_b64 v[162:163], 15, v[158:159]
	v_fmamk_f32 v159, v171, 0x39800000, v170
	v_rsq_f32_e32 v164, v159
	v_lshl_add_u64 v[180:181], s[36:37], 0, v[162:163]
	v_lshlrev_b64 v[162:163], 1, v[160:161]
	v_lshl_add_u64 v[160:161], v[180:181], 0, v[162:163]
	v_pk_fma_f32 v[142:143], v[164:165], v[142:143], v[6:7] op_sel_hi:[0,1,1]
	v_pk_fma_f32 v[140:141], v[164:165], v[140:141], v[4:5] op_sel_hi:[0,1,1]
	v_pk_fma_f32 v[138:139], v[164:165], v[138:139], v[10:11] op_sel_hi:[0,1,1]
	v_pk_fma_f32 v[136:137], v[164:165], v[136:137], v[8:9] op_sel_hi:[0,1,1]
	v_max_f32 v180, 0, v140
	v_max_f32 v181, 0, v141
	v_max_f32 v182, 0, v136
	v_max_f32 v183, 0, v137
	v_max_f32 v184, 0, v142
	v_max_f32 v186, 0, v138
	v_max_f32 v185, 0, v143
	v_max_f32 v187, 0, v139
	s_nop 0
	v_pk_mul_f32 v[140:141], v[140:141], v[180:181]
	v_pk_mul_f32 v[142:143], v[142:143], v[184:185]
	v_pk_mul_f32 v[180:181], v[138:139], v[186:187]
	v_pk_mul_f32 v[138:139], v[136:137], v[182:183]
	v_cvt_pk_bf16_f32 v136, v140, v141
	v_cvt_pk_bf16_f32 v137, v142, v143
	v_pk_fma_f32 v[132:133], v[164:165], v[132:133], v[12:13] op_sel_hi:[0,1,1]
	v_cvt_pk_bf16_f32 v138, v138, v139
	v_cvt_pk_bf16_f32 v139, v180, v181
	global_store_dwordx4 v[160:161], v[136:139], off
	v_pk_fma_f32 v[130:131], v[164:165], v[130:131], v[2:3] op_sel_hi:[0,1,1]
	v_pk_fma_f32 v[128:129], v[164:165], v[128:129], v[0:1] op_sel_hi:[0,1,1]
	v_max_f32 v136, 0, v132
	v_max_f32 v137, 0, v133
	v_max_f32 v138, 0, v128
	v_max_f32 v139, 0, v129
	v_max_f32 v142, 0, v130
	v_max_f32 v143, 0, v131
	v_pk_fma_f32 v[134:135], v[164:165], v[134:135], v[14:15] op_sel_hi:[0,1,1]
	v_pk_mul_f32 v[132:133], v[132:133], v[136:137]
	v_pk_mul_f32 v[136:137], v[130:131], v[142:143]
	v_pk_mul_f32 v[130:131], v[128:129], v[138:139]
	v_max_f32 v140, 0, v134
	v_max_f32 v141, 0, v135
	v_cvt_pk_bf16_f32 v128, v132, v133
	s_nop 0
	v_cvt_pk_bf16_f32 v130, v130, v131
	v_pk_mul_f32 v[134:135], v[134:135], v[140:141]
	v_cvt_pk_bf16_f32 v131, v136, v137
	s_nop 0
	v_cvt_pk_bf16_f32 v129, v134, v135
	global_store_dwordx4 v[160:161], v[128:131], off offset:256
	s_nop 1
	v_fmamk_f32 v130, v174, 0x39800000, v170
	v_rsq_f32_e32 v130, v130
	v_or_b32_e32 v128, 16, v158
	v_ashrrev_i32_e32 v129, 31, v128
	v_lshlrev_b64 v[128:129], 15, v[128:129]
	v_lshl_add_u64 v[128:129], s[36:37], 0, v[128:129]
	v_pk_fma_f32 v[126:127], v[130:131], v[126:127], v[6:7] op_sel_hi:[0,1,1]
	v_pk_fma_f32 v[124:125], v[130:131], v[124:125], v[4:5] op_sel_hi:[0,1,1]
	v_pk_fma_f32 v[122:123], v[130:131], v[122:123], v[10:11] op_sel_hi:[0,1,1]
	v_pk_fma_f32 v[120:121], v[130:131], v[120:121], v[8:9] op_sel_hi:[0,1,1]
	v_max_f32 v132, 0, v124
	v_max_f32 v133, 0, v125
	v_lshl_add_u64 v[128:129], v[128:129], 0, v[162:163]
	v_max_f32 v134, 0, v120
	v_max_f32 v135, 0, v121
	v_max_f32 v136, 0, v126
	v_max_f32 v138, 0, v122
	v_max_f32 v137, 0, v127
	v_max_f32 v139, 0, v123
	v_pk_mul_f32 v[124:125], v[124:125], v[132:133]
	v_pk_mul_f32 v[126:127], v[126:127], v[136:137]
	v_pk_mul_f32 v[132:133], v[122:123], v[138:139]
	v_pk_mul_f32 v[122:123], v[120:121], v[134:135]
	v_cvt_pk_bf16_f32 v120, v124, v125
	v_cvt_pk_bf16_f32 v121, v126, v127
	v_pk_fma_f32 v[116:117], v[130:131], v[116:117], v[12:13] op_sel_hi:[0,1,1]
	v_cvt_pk_bf16_f32 v122, v122, v123
	v_cvt_pk_bf16_f32 v123, v132, v133
	global_store_dwordx4 v[128:129], v[120:123], off
	v_pk_fma_f32 v[114:115], v[130:131], v[114:115], v[2:3] op_sel_hi:[0,1,1]
	v_pk_fma_f32 v[112:113], v[130:131], v[112:113], v[0:1] op_sel_hi:[0,1,1]
	v_max_f32 v120, 0, v116
	v_max_f32 v121, 0, v117
	v_max_f32 v122, 0, v112
	v_max_f32 v123, 0, v113
	v_max_f32 v126, 0, v114
	v_max_f32 v127, 0, v115
	v_pk_fma_f32 v[118:119], v[130:131], v[118:119], v[14:15] op_sel_hi:[0,1,1]
	v_pk_mul_f32 v[116:117], v[116:117], v[120:121]
	v_pk_mul_f32 v[120:121], v[114:115], v[126:127]
	v_pk_mul_f32 v[114:115], v[112:113], v[122:123]
	v_max_f32 v124, 0, v118
	v_max_f32 v125, 0, v119
	v_cvt_pk_bf16_f32 v112, v116, v117
	s_nop 0
	v_cvt_pk_bf16_f32 v114, v114, v115
	v_pk_mul_f32 v[118:119], v[118:119], v[124:125]
	v_cvt_pk_bf16_f32 v115, v120, v121
	s_nop 0
	v_cvt_pk_bf16_f32 v113, v118, v119
	global_store_dwordx4 v[128:129], v[112:115], off offset:256
	s_nop 1
	v_fmamk_f32 v114, v175, 0x39800000, v170
	v_rsq_f32_e32 v114, v114
	v_or_b32_e32 v112, 32, v158
	v_ashrrev_i32_e32 v113, 31, v112
	v_lshlrev_b64 v[112:113], 15, v[112:113]
	v_lshl_add_u64 v[112:113], s[36:37], 0, v[112:113]
	v_pk_fma_f32 v[110:111], v[114:115], v[110:111], v[6:7] op_sel_hi:[0,1,1]
	v_pk_fma_f32 v[108:109], v[114:115], v[108:109], v[4:5] op_sel_hi:[0,1,1]
	v_pk_fma_f32 v[106:107], v[114:115], v[106:107], v[10:11] op_sel_hi:[0,1,1]
	v_pk_fma_f32 v[104:105], v[114:115], v[104:105], v[8:9] op_sel_hi:[0,1,1]
	v_max_f32 v116, 0, v108
	v_max_f32 v117, 0, v109
	v_lshl_add_u64 v[112:113], v[112:113], 0, v[162:163]
	v_max_f32 v118, 0, v104
	v_max_f32 v119, 0, v105
	v_max_f32 v120, 0, v110
	v_max_f32 v122, 0, v106
	v_max_f32 v121, 0, v111
	v_max_f32 v123, 0, v107
	v_pk_mul_f32 v[108:109], v[108:109], v[116:117]
	v_pk_mul_f32 v[110:111], v[110:111], v[120:121]
	v_pk_mul_f32 v[116:117], v[106:107], v[122:123]
	v_pk_mul_f32 v[106:107], v[104:105], v[118:119]
	v_cvt_pk_bf16_f32 v104, v108, v109
	v_cvt_pk_bf16_f32 v105, v110, v111
	v_pk_fma_f32 v[100:101], v[114:115], v[100:101], v[12:13] op_sel_hi:[0,1,1]
	v_cvt_pk_bf16_f32 v106, v106, v107
	v_cvt_pk_bf16_f32 v107, v116, v117
	global_store_dwordx4 v[112:113], v[104:107], off
	v_pk_fma_f32 v[98:99], v[114:115], v[98:99], v[2:3] op_sel_hi:[0,1,1]
	v_pk_fma_f32 v[96:97], v[114:115], v[96:97], v[0:1] op_sel_hi:[0,1,1]
	v_max_f32 v104, 0, v100
	v_max_f32 v105, 0, v101
	v_max_f32 v106, 0, v96
	v_max_f32 v107, 0, v97
	v_max_f32 v110, 0, v98
	v_max_f32 v111, 0, v99
	v_pk_fma_f32 v[102:103], v[114:115], v[102:103], v[14:15] op_sel_hi:[0,1,1]
	v_pk_mul_f32 v[100:101], v[100:101], v[104:105]
	v_pk_mul_f32 v[104:105], v[98:99], v[110:111]
	v_pk_mul_f32 v[98:99], v[96:97], v[106:107]
	v_max_f32 v108, 0, v102
	v_max_f32 v109, 0, v103
	v_cvt_pk_bf16_f32 v96, v100, v101
	s_nop 0
	v_cvt_pk_bf16_f32 v98, v98, v99
	v_pk_mul_f32 v[102:103], v[102:103], v[108:109]
	v_cvt_pk_bf16_f32 v99, v104, v105
	s_nop 0
	v_cvt_pk_bf16_f32 v97, v102, v103
	global_store_dwordx4 v[112:113], v[96:99], off offset:256
	s_nop 1
	v_fmamk_f32 v98, v176, 0x39800000, v170
	v_rsq_f32_e32 v98, v98
	v_or_b32_e32 v96, 48, v158
	v_ashrrev_i32_e32 v97, 31, v96
	v_lshlrev_b64 v[96:97], 15, v[96:97]
	v_lshl_add_u64 v[96:97], s[36:37], 0, v[96:97]
	v_pk_fma_f32 v[94:95], v[98:99], v[94:95], v[6:7] op_sel_hi:[0,1,1]
	v_pk_fma_f32 v[92:93], v[98:99], v[92:93], v[4:5] op_sel_hi:[0,1,1]
	v_pk_fma_f32 v[90:91], v[98:99], v[90:91], v[10:11] op_sel_hi:[0,1,1]
	v_pk_fma_f32 v[88:89], v[98:99], v[88:89], v[8:9] op_sel_hi:[0,1,1]
	v_max_f32 v100, 0, v92
	v_max_f32 v101, 0, v93
	v_lshl_add_u64 v[96:97], v[96:97], 0, v[162:163]
	v_max_f32 v102, 0, v88
	v_max_f32 v103, 0, v89
	v_max_f32 v104, 0, v94
	v_max_f32 v106, 0, v90
	v_max_f32 v105, 0, v95
	v_max_f32 v107, 0, v91
	v_pk_mul_f32 v[92:93], v[92:93], v[100:101]
	v_pk_mul_f32 v[94:95], v[94:95], v[104:105]
	v_pk_mul_f32 v[100:101], v[90:91], v[106:107]
	v_pk_mul_f32 v[90:91], v[88:89], v[102:103]
	v_cvt_pk_bf16_f32 v88, v92, v93
	v_cvt_pk_bf16_f32 v89, v94, v95
	v_pk_fma_f32 v[84:85], v[98:99], v[84:85], v[12:13] op_sel_hi:[0,1,1]
	v_cvt_pk_bf16_f32 v90, v90, v91
	v_cvt_pk_bf16_f32 v91, v100, v101
	global_store_dwordx4 v[96:97], v[88:91], off
	v_pk_fma_f32 v[82:83], v[98:99], v[82:83], v[2:3] op_sel_hi:[0,1,1]
	v_pk_fma_f32 v[80:81], v[98:99], v[80:81], v[0:1] op_sel_hi:[0,1,1]
	v_max_f32 v88, 0, v84
	v_max_f32 v89, 0, v85
	v_max_f32 v90, 0, v80
	v_max_f32 v91, 0, v81
	v_max_f32 v94, 0, v82
	v_max_f32 v95, 0, v83
	v_pk_fma_f32 v[86:87], v[98:99], v[86:87], v[14:15] op_sel_hi:[0,1,1]
	v_pk_mul_f32 v[84:85], v[84:85], v[88:89]
	v_pk_mul_f32 v[88:89], v[82:83], v[94:95]
	v_pk_mul_f32 v[82:83], v[80:81], v[90:91]
	v_cvt_pk_bf16_f32 v80, v84, v85
	v_max_f32 v92, 0, v86
	v_max_f32 v93, 0, v87
	s_nop 0
	v_cvt_pk_bf16_f32 v82, v82, v83
	v_fmamk_f32 v83, v178, 0x39800000, v170
	v_rsq_f32_e32 v84, v83
	v_cvt_pk_bf16_f32 v83, v88, v89
	v_pk_mul_f32 v[86:87], v[86:87], v[92:93]
	v_pk_fma_f32 v[76:77], v[84:85], v[76:77], v[4:5] op_sel_hi:[0,1,1]
	v_cvt_pk_bf16_f32 v81, v86, v87
	global_store_dwordx4 v[96:97], v[80:83], off offset:256
	v_pk_fma_f32 v[74:75], v[84:85], v[74:75], v[10:11] op_sel_hi:[0,1,1]
	v_pk_fma_f32 v[72:73], v[84:85], v[72:73], v[8:9] op_sel_hi:[0,1,1]
	v_max_f32 v82, 0, v76
	v_max_f32 v83, 0, v77
	v_pk_fma_f32 v[78:79], v[84:85], v[78:79], v[6:7] op_sel_hi:[0,1,1]
	v_pk_mul_f32 v[76:77], v[76:77], v[82:83]
	v_max_f32 v86, 0, v72
	v_max_f32 v87, 0, v73
	v_max_f32 v90, 0, v74
	v_max_f32 v91, 0, v75
	v_max_f32 v88, 0, v78
	v_max_f32 v89, 0, v79
	v_pk_fma_f32 v[68:69], v[84:85], v[68:69], v[12:13] op_sel_hi:[0,1,1]
	v_pk_mul_f32 v[82:83], v[74:75], v[90:91]
	v_pk_mul_f32 v[74:75], v[72:73], v[86:87]
	v_cvt_pk_bf16_f32 v72, v76, v77
	v_add_co_u32_e32 v76, vcc, s59, v160
	v_pk_mul_f32 v[78:79], v[78:79], v[88:89]
	s_nop 0
	v_addc_co_u32_e32 v77, vcc, 0, v161, vcc
	v_cvt_pk_bf16_f32 v73, v78, v79
	v_cvt_pk_bf16_f32 v74, v74, v75
	v_cvt_pk_bf16_f32 v75, v82, v83
	global_store_dwordx4 v[76:77], v[72:75], off
	v_pk_fma_f32 v[66:67], v[84:85], v[66:67], v[2:3] op_sel_hi:[0,1,1]
	v_pk_fma_f32 v[64:65], v[84:85], v[64:65], v[0:1] op_sel_hi:[0,1,1]
	v_max_f32 v72, 0, v68
	v_max_f32 v73, 0, v69
	v_max_f32 v74, 0, v64
	v_max_f32 v75, 0, v65
	v_max_f32 v78, 0, v66
	v_max_f32 v79, 0, v67
	v_lshl_add_u64 v[80:81], v[160:161], 0, s[14:15]
	v_pk_mul_f32 v[68:69], v[68:69], v[72:73]
	v_pk_mul_f32 v[72:73], v[66:67], v[78:79]
	v_pk_mul_f32 v[66:67], v[64:65], v[74:75]
	v_cvt_pk_bf16_f32 v64, v68, v69
	v_pk_fma_f32 v[70:71], v[84:85], v[70:71], v[14:15] op_sel_hi:[0,1,1]
	v_cvt_pk_bf16_f32 v66, v66, v67
	v_fmamk_f32 v67, v173, 0x39800000, v170
	v_rsq_f32_e32 v68, v67
	v_cvt_pk_bf16_f32 v67, v72, v73
	v_max_f32 v76, 0, v70
	v_max_f32 v77, 0, v71
	s_nop 0
	v_pk_fma_f32 v[60:61], v[68:69], v[60:61], v[4:5] op_sel_hi:[0,1,1]
	v_pk_mul_f32 v[70:71], v[70:71], v[76:77]
	v_pk_fma_f32 v[58:59], v[68:69], v[58:59], v[10:11] op_sel_hi:[0,1,1]
	v_cvt_pk_bf16_f32 v65, v70, v71
	global_store_dwordx4 v[80:81], v[64:67], off offset:256
	v_pk_fma_f32 v[56:57], v[68:69], v[56:57], v[8:9] op_sel_hi:[0,1,1]
	v_pk_fma_f32 v[62:63], v[68:69], v[62:63], v[6:7] op_sel_hi:[0,1,1]
	v_max_f32 v66, 0, v60
	v_max_f32 v67, 0, v61
	v_max_f32 v70, 0, v56
	v_max_f32 v71, 0, v57
	v_max_f32 v74, 0, v58
	v_max_f32 v75, 0, v59
	v_max_f32 v72, 0, v62
	s_nop 0
	v_pk_mul_f32 v[60:61], v[60:61], v[66:67]
	v_pk_mul_f32 v[66:67], v[58:59], v[74:75]
	v_pk_mul_f32 v[58:59], v[56:57], v[70:71]
	v_cvt_pk_bf16_f32 v56, v60, v61
	v_add_co_u32_e32 v60, vcc, s60, v160
	v_max_f32 v73, 0, v63
	v_cvt_pk_bf16_f32 v58, v58, v59
	v_cvt_pk_bf16_f32 v59, v66, v67
	v_pk_fma_f32 v[52:53], v[68:69], v[52:53], v[12:13] op_sel_hi:[0,1,1]
	v_pk_mul_f32 v[62:63], v[62:63], v[72:73]
	v_addc_co_u32_e32 v61, vcc, 0, v161, vcc
	v_cvt_pk_bf16_f32 v57, v62, v63
	global_store_dwordx4 v[60:61], v[56:59], off
	v_pk_fma_f32 v[50:51], v[68:69], v[50:51], v[2:3] op_sel_hi:[0,1,1]
	v_pk_fma_f32 v[48:49], v[68:69], v[48:49], v[0:1] op_sel_hi:[0,1,1]
	v_max_f32 v56, 0, v52
	v_max_f32 v57, 0, v53
	v_max_f32 v58, 0, v48
	v_max_f32 v59, 0, v49
	v_max_f32 v62, 0, v50
	v_max_f32 v63, 0, v51
	v_lshl_add_u64 v[64:65], v[160:161], 0, s[16:17]
	v_pk_mul_f32 v[52:53], v[52:53], v[56:57]
	v_pk_mul_f32 v[56:57], v[50:51], v[62:63]
	v_pk_mul_f32 v[50:51], v[48:49], v[58:59]
	v_cvt_pk_bf16_f32 v48, v52, v53
	v_pk_fma_f32 v[54:55], v[68:69], v[54:55], v[14:15] op_sel_hi:[0,1,1]
	v_cvt_pk_bf16_f32 v50, v50, v51
	v_fmamk_f32 v51, v172, 0x39800000, v170
	v_rsq_f32_e32 v52, v51
	v_cvt_pk_bf16_f32 v51, v56, v57
	v_max_f32 v60, 0, v54
	v_max_f32 v61, 0, v55
	s_nop 0
	v_pk_fma_f32 v[44:45], v[52:53], v[44:45], v[4:5] op_sel_hi:[0,1,1]
	v_pk_mul_f32 v[54:55], v[54:55], v[60:61]
	v_pk_fma_f32 v[42:43], v[52:53], v[42:43], v[10:11] op_sel_hi:[0,1,1]
	v_cvt_pk_bf16_f32 v49, v54, v55
	global_store_dwordx4 v[64:65], v[48:51], off offset:256
	v_pk_fma_f32 v[40:41], v[52:53], v[40:41], v[8:9] op_sel_hi:[0,1,1]
	v_pk_fma_f32 v[46:47], v[52:53], v[46:47], v[6:7] op_sel_hi:[0,1,1]
	v_max_f32 v50, 0, v44
	v_max_f32 v51, 0, v45
	v_max_f32 v54, 0, v40
	v_max_f32 v55, 0, v41
	v_max_f32 v58, 0, v42
	v_max_f32 v59, 0, v43
	v_max_f32 v56, 0, v46
	s_nop 0
	v_pk_mul_f32 v[44:45], v[44:45], v[50:51]
	v_pk_mul_f32 v[50:51], v[42:43], v[58:59]
	v_pk_mul_f32 v[42:43], v[40:41], v[54:55]
	v_cvt_pk_bf16_f32 v40, v44, v45
	v_add_co_u32_e32 v44, vcc, s61, v160
	v_max_f32 v57, 0, v47
	v_cvt_pk_bf16_f32 v42, v42, v43
	v_cvt_pk_bf16_f32 v43, v50, v51
	v_pk_fma_f32 v[36:37], v[52:53], v[36:37], v[12:13] op_sel_hi:[0,1,1]
	v_pk_mul_f32 v[46:47], v[46:47], v[56:57]
	v_addc_co_u32_e32 v45, vcc, 0, v161, vcc
	v_cvt_pk_bf16_f32 v41, v46, v47
	global_store_dwordx4 v[44:45], v[40:43], off
	v_pk_fma_f32 v[34:35], v[52:53], v[34:35], v[2:3] op_sel_hi:[0,1,1]
	v_pk_fma_f32 v[32:33], v[52:53], v[32:33], v[0:1] op_sel_hi:[0,1,1]
	v_max_f32 v40, 0, v36
	v_max_f32 v41, 0, v37
	v_max_f32 v42, 0, v32
	v_max_f32 v43, 0, v33
	v_max_f32 v46, 0, v34
	v_max_f32 v47, 0, v35
	v_lshl_add_u64 v[48:49], v[160:161], 0, s[18:19]
	v_pk_mul_f32 v[36:37], v[36:37], v[40:41]
	v_pk_mul_f32 v[40:41], v[34:35], v[46:47]
	v_pk_mul_f32 v[34:35], v[32:33], v[42:43]
	v_cvt_pk_bf16_f32 v32, v36, v37
	v_pk_fma_f32 v[38:39], v[52:53], v[38:39], v[14:15] op_sel_hi:[0,1,1]
	v_cvt_pk_bf16_f32 v34, v34, v35
	v_fmamk_f32 v35, v177, 0x39800000, v170
	v_rsq_f32_e32 v36, v35
	v_cvt_pk_bf16_f32 v35, v40, v41
	v_max_f32 v44, 0, v38
	v_max_f32 v45, 0, v39
	s_nop 0
	v_pk_fma_f32 v[28:29], v[36:37], v[28:29], v[4:5] op_sel_hi:[0,1,1]
	v_pk_mul_f32 v[38:39], v[38:39], v[44:45]
	v_pk_fma_f32 v[26:27], v[36:37], v[26:27], v[10:11] op_sel_hi:[0,1,1]
	v_cvt_pk_bf16_f32 v33, v38, v39
	global_store_dwordx4 v[48:49], v[32:35], off offset:256
	v_pk_fma_f32 v[24:25], v[36:37], v[24:25], v[8:9] op_sel_hi:[0,1,1]
	v_pk_fma_f32 v[30:31], v[36:37], v[30:31], v[6:7] op_sel_hi:[0,1,1]
	v_max_f32 v34, 0, v28
	v_max_f32 v35, 0, v29
	v_max_f32 v38, 0, v24
	v_max_f32 v39, 0, v25
	v_max_f32 v42, 0, v26
	v_max_f32 v43, 0, v27
	v_max_f32 v40, 0, v30
	s_nop 0
	v_pk_mul_f32 v[28:29], v[28:29], v[34:35]
	v_pk_mul_f32 v[34:35], v[26:27], v[42:43]
	v_pk_mul_f32 v[26:27], v[24:25], v[38:39]
	v_cvt_pk_bf16_f32 v24, v28, v29
	v_add_co_u32_e32 v28, vcc, s62, v160
	v_max_f32 v41, 0, v31
	v_cvt_pk_bf16_f32 v26, v26, v27
	v_cvt_pk_bf16_f32 v27, v34, v35
	v_pk_fma_f32 v[20:21], v[36:37], v[20:21], v[12:13] op_sel_hi:[0,1,1]
	v_pk_mul_f32 v[30:31], v[30:31], v[40:41]
	v_addc_co_u32_e32 v29, vcc, 0, v161, vcc
	v_cvt_pk_bf16_f32 v25, v30, v31
	global_store_dwordx4 v[28:29], v[24:27], off
	v_pk_fma_f32 v[18:19], v[36:37], v[18:19], v[2:3] op_sel_hi:[0,1,1]
	v_pk_fma_f32 v[16:17], v[36:37], v[16:17], v[0:1] op_sel_hi:[0,1,1]
	v_max_f32 v24, 0, v20
	v_max_f32 v25, 0, v21
	v_lshl_add_u64 v[32:33], v[160:161], 0, s[20:21]
	v_pk_fma_f32 v[22:23], v[36:37], v[22:23], v[14:15] op_sel_hi:[0,1,1]
	v_max_f32 v26, 0, v16
	v_max_f32 v27, 0, v17
	v_max_f32 v30, 0, v18
	v_max_f32 v31, 0, v19
	v_pk_mul_f32 v[20:21], v[20:21], v[24:25]
	v_pk_mul_f32 v[24:25], v[18:19], v[30:31]
	v_pk_mul_f32 v[18:19], v[16:17], v[26:27]
	s_andn2_b64 vcc, exec, s[0:1]
	s_mov_b64 s[0:1], -1
	v_max_f32 v28, 0, v22
	v_max_f32 v29, 0, v23
	v_cvt_pk_bf16_f32 v16, v20, v21
	v_cvt_pk_bf16_f32 v18, v18, v19
	v_cvt_pk_bf16_f32 v19, v24, v25
	s_nop 0
	v_pk_mul_f32 v[22:23], v[22:23], v[28:29]
	s_nop 0
	v_cvt_pk_bf16_f32 v17, v22, v23
	global_store_dwordx4 v[32:33], v[16:19], off offset:256
	s_cbranch_vccnz .LBB8_1044
	s_andn2_b64 vcc, exec, s[8:9]
	s_cbranch_vccnz .LBB8_1043
	s_barrier
	s_branch .LBB8_1043

.LBB8_1133:
	ds_read_b128 v[76:79], v165
	ds_read_b128 v[84:87], v165 offset:1024
	ds_read_b128 v[96:99], v165 offset:2048
	ds_read_b128 v[108:111], v165 offset:3072
	ds_read_b128 v[156:159], v166
	ds_read_b128 v[168:171], v166 offset:1024
	ds_read_b128 v[172:175], v166 offset:2048
	ds_read_b128 v[176:179], v166 offset:3072
	s_add_u32 s30, s26, 0xffc00080
	s_addc_u32 s31, s27, -1
	s_cmpk_eq_i32 s57, 0xfc
	s_cselect_b32 s35, s21, s31
	s_cselect_b32 s34, s53, s30
	s_cselect_b32 s31, s19, s56
	s_cselect_b32 s30, s54, s55
	v_lshl_add_u64 v[160:161], s[26:27], 0, v[148:149]
	s_add_i32 m0, s29, 0xc000
	ds_read_b128 v[180:183], v167
	ds_read_b128 v[184:187], v167 offset:1024
	ds_read_b128 v[188:191], v167 offset:2048
	ds_read_b128 v[192:195], v167 offset:3072
	ds_read_b128 v[196:199], v167 offset:4096
	ds_read_b128 v[200:203], v167 offset:5120
	ds_read_b128 v[204:207], v167 offset:6144
	ds_read_b128 v[208:211], v167 offset:7168
	global_load_lds_dwordx4 v[160:161], off
	v_lshl_add_u64 v[160:161], s[26:27], 0, v[150:151]
	s_add_i32 m0, s29, 0xe000
	s_nop 0
	global_load_lds_dwordx4 v[160:161], off
	s_waitcnt vmcnt(8)
	s_waitcnt lgkmcnt(0)
	s_setprio 1
	s_barrier
	v_mfma_f32_16x16x32_bf16 v[140:143], v[76:79], v[180:183], v[140:143]
	v_mfma_f32_16x16x32_bf16 v[136:139], v[96:99], v[180:183], v[136:139]
	v_mfma_f32_16x16x32_bf16 v[132:135], v[76:79], v[188:191], v[132:135]
	v_mfma_f32_16x16x32_bf16 v[128:131], v[96:99], v[188:191], v[128:131]
	v_mfma_f32_16x16x32_bf16 v[120:123], v[76:79], v[196:199], v[120:123]
	v_mfma_f32_16x16x32_bf16 v[112:115], v[96:99], v[196:199], v[112:115]
	v_mfma_f32_16x16x32_bf16 v[100:103], v[76:79], v[204:207], v[100:103]
	v_mfma_f32_16x16x32_bf16 v[88:91], v[96:99], v[204:207], v[88:91]
	v_mfma_f32_16x16x32_bf16 v[140:143], v[84:87], v[184:187], v[140:143]
	v_mfma_f32_16x16x32_bf16 v[136:139], v[108:111], v[184:187], v[136:139]
	v_mfma_f32_16x16x32_bf16 v[132:135], v[84:87], v[192:195], v[132:135]
	v_mfma_f32_16x16x32_bf16 v[128:131], v[108:111], v[192:195], v[128:131]
	v_mfma_f32_16x16x32_bf16 v[120:123], v[84:87], v[200:203], v[120:123]
	v_mfma_f32_16x16x32_bf16 v[112:115], v[108:111], v[200:203], v[112:115]
	v_mfma_f32_16x16x32_bf16 v[100:103], v[84:87], v[208:211], v[100:103]
	v_mfma_f32_16x16x32_bf16 v[88:91], v[108:111], v[208:211], v[88:91]
	v_mfma_f32_16x16x32_bf16 v[124:127], v[156:159], v[180:183], v[124:127]
	v_mfma_f32_16x16x32_bf16 v[116:119], v[172:175], v[180:183], v[116:119]
	v_mfma_f32_16x16x32_bf16 v[104:107], v[156:159], v[188:191], v[104:107]
	v_mfma_f32_16x16x32_bf16 v[92:95], v[172:175], v[188:191], v[92:95]
	v_mfma_f32_16x16x32_bf16 v[80:83], v[156:159], v[196:199], v[80:83]
	v_mfma_f32_16x16x32_bf16 v[72:75], v[172:175], v[196:199], v[72:75]
	v_mfma_f32_16x16x32_bf16 v[68:71], v[156:159], v[204:207], v[68:71]
	v_mfma_f32_16x16x32_bf16 v[64:67], v[172:175], v[204:207], v[64:67]
	v_mfma_f32_16x16x32_bf16 v[124:127], v[168:171], v[184:187], v[124:127]
	v_mfma_f32_16x16x32_bf16 v[116:119], v[176:179], v[184:187], v[116:119]
	v_mfma_f32_16x16x32_bf16 v[104:107], v[168:171], v[192:195], v[104:107]
	v_mfma_f32_16x16x32_bf16 v[92:95], v[176:179], v[192:195], v[92:95]
	v_mfma_f32_16x16x32_bf16 v[80:83], v[168:171], v[200:203], v[80:83]
	v_mfma_f32_16x16x32_bf16 v[72:75], v[176:179], v[200:203], v[72:75]
	v_mfma_f32_16x16x32_bf16 v[68:71], v[168:171], v[208:211], v[68:71]
	v_mfma_f32_16x16x32_bf16 v[64:67], v[176:179], v[208:211], v[64:67]
	s_barrier
	s_setprio 0
	s_add_i32 s58, s48, s38
	v_lshl_add_u64 v[160:161], s[30:31], 0, v[144:145]
	s_mov_b32 m0, s58
	ds_read_b128 v[180:183], v167 offset:16384
	ds_read_b128 v[184:187], v167 offset:17408
	ds_read_b128 v[188:191], v167 offset:18432
	ds_read_b128 v[192:195], v167 offset:19456
	ds_read_b128 v[196:199], v167 offset:20480
	ds_read_b128 v[200:203], v167 offset:21504
	ds_read_b128 v[204:207], v167 offset:22528
	ds_read_b128 v[208:211], v167 offset:23552
	global_load_lds_dwordx4 v[160:161], off
	s_add_i32 m0, s58, 0x2000
	s_add_u32 s58, s30, 0x400000
	v_lshl_add_u64 v[212:213], s[30:31], 0, v[146:147]
	s_addc_u32 s59, s31, 0
	s_add_i32 s60, s49, s38
	global_load_lds_dwordx4 v[212:213], off
	v_lshl_add_u64 v[214:215], s[58:59], 0, v[144:145]
	s_mov_b32 m0, s60
	v_lshl_add_u64 v[216:217], s[34:35], 0, v[146:147]
	global_load_lds_dwordx4 v[214:215], off
	v_lshl_add_u64 v[214:215], s[58:59], 0, v[146:147]
	s_add_i32 m0, s60, 0x2000
	s_nop 0
	global_load_lds_dwordx4 v[214:215], off
	v_lshl_add_u64 v[214:215], s[34:35], 0, v[144:145]
	s_mov_b32 m0, s29
	s_nop 0
	global_load_lds_dwordx4 v[214:215], off
	s_mov_b32 m0, s39
	s_nop 0
	global_load_lds_dwordx4 v[216:217], off
	s_waitcnt vmcnt(8)
	s_waitcnt lgkmcnt(0)
	s_setprio 1
	s_barrier
	v_mfma_f32_16x16x32_bf16 v[60:63], v[76:79], v[180:183], v[60:63]
	v_mfma_f32_16x16x32_bf16 v[56:59], v[96:99], v[180:183], v[56:59]
	v_mfma_f32_16x16x32_bf16 v[52:55], v[76:79], v[188:191], v[52:55]
	v_mfma_f32_16x16x32_bf16 v[44:47], v[96:99], v[188:191], v[44:47]
	v_mfma_f32_16x16x32_bf16 v[36:39], v[76:79], v[196:199], v[36:39]
	v_mfma_f32_16x16x32_bf16 v[28:31], v[96:99], v[196:199], v[28:31]
	v_mfma_f32_16x16x32_bf16 v[20:23], v[76:79], v[204:207], v[20:23]
	v_mfma_f32_16x16x32_bf16 v[12:15], v[96:99], v[204:207], v[12:15]
	v_mfma_f32_16x16x32_bf16 v[60:63], v[84:87], v[184:187], v[60:63]
	v_mfma_f32_16x16x32_bf16 v[56:59], v[108:111], v[184:187], v[56:59]
	v_mfma_f32_16x16x32_bf16 v[52:55], v[84:87], v[192:195], v[52:55]
	v_mfma_f32_16x16x32_bf16 v[44:47], v[108:111], v[192:195], v[44:47]
	v_mfma_f32_16x16x32_bf16 v[36:39], v[84:87], v[200:203], v[36:39]
	v_mfma_f32_16x16x32_bf16 v[28:31], v[108:111], v[200:203], v[28:31]
	v_mfma_f32_16x16x32_bf16 v[20:23], v[84:87], v[208:211], v[20:23]
	v_mfma_f32_16x16x32_bf16 v[12:15], v[108:111], v[208:211], v[12:15]
	v_mfma_f32_16x16x32_bf16 v[48:51], v[156:159], v[180:183], v[48:51]
	v_mfma_f32_16x16x32_bf16 v[40:43], v[172:175], v[180:183], v[40:43]
	v_mfma_f32_16x16x32_bf16 v[32:35], v[156:159], v[188:191], v[32:35]
	v_mfma_f32_16x16x32_bf16 v[24:27], v[172:175], v[188:191], v[24:27]
	v_mfma_f32_16x16x32_bf16 v[16:19], v[156:159], v[196:199], v[16:19]
	v_mfma_f32_16x16x32_bf16 v[8:11], v[172:175], v[196:199], v[8:11]
	v_mfma_f32_16x16x32_bf16 v[4:7], v[156:159], v[204:207], v[4:7]
	v_mfma_f32_16x16x32_bf16 v[0:3], v[172:175], v[204:207], v[0:3]
	v_mfma_f32_16x16x32_bf16 v[48:51], v[168:171], v[184:187], v[48:51]
	v_mfma_f32_16x16x32_bf16 v[40:43], v[176:179], v[184:187], v[40:43]
	v_mfma_f32_16x16x32_bf16 v[32:35], v[168:171], v[192:195], v[32:35]
	v_mfma_f32_16x16x32_bf16 v[24:27], v[176:179], v[192:195], v[24:27]
	v_mfma_f32_16x16x32_bf16 v[16:19], v[168:171], v[200:203], v[16:19]
	v_mfma_f32_16x16x32_bf16 v[8:11], v[176:179], v[200:203], v[8:11]
	v_mfma_f32_16x16x32_bf16 v[4:7], v[168:171], v[208:211], v[4:7]
	v_mfma_f32_16x16x32_bf16 v[0:3], v[176:179], v[208:211], v[0:3]
	s_barrier
	s_setprio 0
	s_add_i32 s58, 0, 0x18000
	s_add_i32 s59, 0, 0x1c000
	v_add_u32_e32 v108, s58, v163
	v_add_u32_e32 v176, s59, v163
	ds_read_b128 v[76:79], v108
	ds_read_b128 v[84:87], v108 offset:1024
	ds_read_b128 v[96:99], v108 offset:2048
	ds_read_b128 v[108:111], v108 offset:3072
	ds_read_b128 v[156:159], v176
	ds_read_b128 v[168:171], v176 offset:1024
	ds_read_b128 v[172:175], v176 offset:2048
	ds_read_b128 v[176:179], v176 offset:3072
	s_add_u32 s34, s34, 0x400000
	s_addc_u32 s35, s35, 0
	s_mov_b32 m0, s40
	v_lshl_add_u64 v[218:219], s[34:35], 0, v[144:145]
	ds_read_b128 v[180:183], v167 offset:32768
	ds_read_b128 v[184:187], v167 offset:33792
	ds_read_b128 v[188:191], v167 offset:34816
	ds_read_b128 v[192:195], v167 offset:35840
	ds_read_b128 v[196:199], v167 offset:36864
	ds_read_b128 v[200:203], v167 offset:37888
	ds_read_b128 v[204:207], v167 offset:38912
	ds_read_b128 v[208:211], v167 offset:39936
	global_load_lds_dwordx4 v[218:219], off
	v_lshl_add_u64 v[218:219], s[34:35], 0, v[146:147]
	s_mov_b32 m0, s41
	s_nop 0
	global_load_lds_dwordx4 v[218:219], off
	s_waitcnt vmcnt(8)
	s_waitcnt lgkmcnt(0)
	s_setprio 1
	s_barrier
	v_mfma_f32_16x16x32_bf16 v[140:143], v[76:79], v[180:183], v[140:143]
	v_mfma_f32_16x16x32_bf16 v[136:139], v[96:99], v[180:183], v[136:139]
	v_mfma_f32_16x16x32_bf16 v[132:135], v[76:79], v[188:191], v[132:135]
	v_mfma_f32_16x16x32_bf16 v[128:131], v[96:99], v[188:191], v[128:131]
	v_mfma_f32_16x16x32_bf16 v[120:123], v[76:79], v[196:199], v[120:123]
	v_mfma_f32_16x16x32_bf16 v[112:115], v[96:99], v[196:199], v[112:115]
	v_mfma_f32_16x16x32_bf16 v[100:103], v[76:79], v[204:207], v[100:103]
	v_mfma_f32_16x16x32_bf16 v[88:91], v[96:99], v[204:207], v[88:91]
	v_mfma_f32_16x16x32_bf16 v[140:143], v[84:87], v[184:187], v[140:143]
	v_mfma_f32_16x16x32_bf16 v[136:139], v[108:111], v[184:187], v[136:139]
	v_mfma_f32_16x16x32_bf16 v[132:135], v[84:87], v[192:195], v[132:135]
	v_mfma_f32_16x16x32_bf16 v[128:131], v[108:111], v[192:195], v[128:131]
	v_mfma_f32_16x16x32_bf16 v[120:123], v[84:87], v[200:203], v[120:123]
	v_mfma_f32_16x16x32_bf16 v[112:115], v[108:111], v[200:203], v[112:115]
	v_mfma_f32_16x16x32_bf16 v[100:103], v[84:87], v[208:211], v[100:103]
	v_mfma_f32_16x16x32_bf16 v[88:91], v[108:111], v[208:211], v[88:91]
	v_mfma_f32_16x16x32_bf16 v[124:127], v[156:159], v[180:183], v[124:127]
	v_mfma_f32_16x16x32_bf16 v[116:119], v[172:175], v[180:183], v[116:119]
	v_mfma_f32_16x16x32_bf16 v[104:107], v[156:159], v[188:191], v[104:107]
	v_mfma_f32_16x16x32_bf16 v[92:95], v[172:175], v[188:191], v[92:95]
	v_mfma_f32_16x16x32_bf16 v[80:83], v[156:159], v[196:199], v[80:83]
	v_mfma_f32_16x16x32_bf16 v[72:75], v[172:175], v[196:199], v[72:75]
	v_mfma_f32_16x16x32_bf16 v[68:71], v[156:159], v[204:207], v[68:71]
	v_mfma_f32_16x16x32_bf16 v[64:67], v[172:175], v[204:207], v[64:67]
	v_mfma_f32_16x16x32_bf16 v[124:127], v[168:171], v[184:187], v[124:127]
	v_mfma_f32_16x16x32_bf16 v[116:119], v[176:179], v[184:187], v[116:119]
	v_mfma_f32_16x16x32_bf16 v[104:107], v[168:171], v[192:195], v[104:107]
	v_mfma_f32_16x16x32_bf16 v[92:95], v[176:179], v[192:195], v[92:95]
	v_mfma_f32_16x16x32_bf16 v[80:83], v[168:171], v[200:203], v[80:83]
	v_mfma_f32_16x16x32_bf16 v[72:75], v[176:179], v[200:203], v[72:75]
	v_mfma_f32_16x16x32_bf16 v[68:71], v[168:171], v[208:211], v[68:71]
	v_mfma_f32_16x16x32_bf16 v[64:67], v[176:179], v[208:211], v[64:67]
	s_barrier
	s_setprio 0
	s_add_i32 s34, s58, s38
	v_lshl_add_u64 v[160:161], v[160:161], 0, s[6:7]
	s_mov_b32 m0, s34
	ds_read_b128 v[180:183], v167 offset:49152
	ds_read_b128 v[184:187], v167 offset:50176
	ds_read_b128 v[188:191], v167 offset:51200
	ds_read_b128 v[192:195], v167 offset:52224
	ds_read_b128 v[196:199], v167 offset:53248
	ds_read_b128 v[200:203], v167 offset:54272
	ds_read_b128 v[204:207], v167 offset:55296
	ds_read_b128 v[208:211], v167 offset:56320
	global_load_lds_dwordx4 v[160:161], off
	s_add_i32 m0, s34, 0x2000
	s_add_u32 s30, s30, 0x400080
	v_lshl_add_u64 v[160:161], v[212:213], 0, s[6:7]
	s_addc_u32 s31, s31, 0
	s_add_i32 s34, s59, s38
	global_load_lds_dwordx4 v[160:161], off
	v_lshl_add_u64 v[160:161], s[30:31], 0, v[144:145]
	s_mov_b32 m0, s34
	s_nop 0
	global_load_lds_dwordx4 v[160:161], off
	v_lshl_add_u64 v[160:161], s[30:31], 0, v[146:147]
	s_add_i32 m0, s34, 0x2000
	s_nop 0
	global_load_lds_dwordx4 v[160:161], off
	v_lshl_add_u64 v[160:161], v[214:215], 0, s[6:7]
	s_mov_b32 m0, s45
	s_nop 0
	global_load_lds_dwordx4 v[160:161], off
	v_lshl_add_u64 v[160:161], v[216:217], 0, s[6:7]
	s_mov_b32 m0, s46
	s_nop 0
	global_load_lds_dwordx4 v[160:161], off
	s_waitcnt vmcnt(8)
	s_waitcnt lgkmcnt(0)
	s_setprio 1
	s_barrier
	v_mfma_f32_16x16x32_bf16 v[60:63], v[76:79], v[180:183], v[60:63]
	v_mfma_f32_16x16x32_bf16 v[56:59], v[96:99], v[180:183], v[56:59]
	v_mfma_f32_16x16x32_bf16 v[52:55], v[76:79], v[188:191], v[52:55]
	v_mfma_f32_16x16x32_bf16 v[44:47], v[96:99], v[188:191], v[44:47]
	v_mfma_f32_16x16x32_bf16 v[36:39], v[76:79], v[196:199], v[36:39]
	v_mfma_f32_16x16x32_bf16 v[28:31], v[96:99], v[196:199], v[28:31]
	v_mfma_f32_16x16x32_bf16 v[20:23], v[76:79], v[204:207], v[20:23]
	v_mfma_f32_16x16x32_bf16 v[12:15], v[96:99], v[204:207], v[12:15]
	v_mfma_f32_16x16x32_bf16 v[60:63], v[84:87], v[184:187], v[60:63]
	v_mfma_f32_16x16x32_bf16 v[56:59], v[108:111], v[184:187], v[56:59]
	v_mfma_f32_16x16x32_bf16 v[52:55], v[84:87], v[192:195], v[52:55]
	v_mfma_f32_16x16x32_bf16 v[44:47], v[108:111], v[192:195], v[44:47]
	v_mfma_f32_16x16x32_bf16 v[36:39], v[84:87], v[200:203], v[36:39]
	v_mfma_f32_16x16x32_bf16 v[28:31], v[108:111], v[200:203], v[28:31]
	v_mfma_f32_16x16x32_bf16 v[20:23], v[84:87], v[208:211], v[20:23]
	v_mfma_f32_16x16x32_bf16 v[12:15], v[108:111], v[208:211], v[12:15]
	v_mfma_f32_16x16x32_bf16 v[48:51], v[156:159], v[180:183], v[48:51]
	v_mfma_f32_16x16x32_bf16 v[40:43], v[172:175], v[180:183], v[40:43]
	v_mfma_f32_16x16x32_bf16 v[32:35], v[156:159], v[188:191], v[32:35]
	v_mfma_f32_16x16x32_bf16 v[24:27], v[172:175], v[188:191], v[24:27]
	v_mfma_f32_16x16x32_bf16 v[16:19], v[156:159], v[196:199], v[16:19]
	v_mfma_f32_16x16x32_bf16 v[8:11], v[172:175], v[196:199], v[8:11]
	v_mfma_f32_16x16x32_bf16 v[4:7], v[156:159], v[204:207], v[4:7]
	v_mfma_f32_16x16x32_bf16 v[0:3], v[172:175], v[204:207], v[0:3]
	v_mfma_f32_16x16x32_bf16 v[48:51], v[168:171], v[184:187], v[48:51]
	v_mfma_f32_16x16x32_bf16 v[40:43], v[176:179], v[184:187], v[40:43]
	v_mfma_f32_16x16x32_bf16 v[32:35], v[168:171], v[192:195], v[32:35]
	v_mfma_f32_16x16x32_bf16 v[24:27], v[176:179], v[192:195], v[24:27]
	v_mfma_f32_16x16x32_bf16 v[16:19], v[168:171], v[200:203], v[16:19]
	v_mfma_f32_16x16x32_bf16 v[8:11], v[176:179], v[200:203], v[8:11]
	v_mfma_f32_16x16x32_bf16 v[4:7], v[168:171], v[208:211], v[4:7]
	v_mfma_f32_16x16x32_bf16 v[0:3], v[176:179], v[208:211], v[0:3]
	s_barrier
	s_setprio 0
	s_add_i32 s57, s57, 2
	s_add_u32 s26, s26, 0x100
	s_addc_u32 s27, s27, 0
	s_add_u32 s55, s55, 0x100
	s_addc_u32 s56, s56, 0
	s_cmpk_gt_u32 s57, 0xfd
	s_cbranch_scc0 .LBB8_1133
	s_and_b64 vcc, exec, s[8:9]
	s_cbranch_vccz .LBB8_1136
	s_barrier
